# attention far tiles: resident Q fragments, constant bias through the MFMA C operand (no per-element adds), both tiles exp in place
# speedup vs baseline: 1.0188x; 1.0144x over previous
.LBB0_578:
	s_or_b64 exec, exec, s[68:69]
	s_mov_b32 s41, s53
	s_lshl_b64 s[68:69], s[40:41], 10
	s_add_u32 s37, s46, s68
	s_addc_u32 s48, s47, s69
	s_lshl_b32 s3, s22, 1
	s_add_u32 s37, s37, s3
	s_addc_u32 s48, s48, 0
	s_add_u32 s60, s37, 0xab00000
	s_addc_u32 s61, s48, 0
	v_and_b32_e32 v27, 15, v18
	v_lshlrev_b64 v[32:33], 10, v[22:23]
	s_lshl_b32 s52, s22, 16
	v_lshlrev_b32_e32 v176, 4, v27
	v_lshl_add_u64 v[32:33], s[60:61], 0, v[32:33]
	s_add_u32 s37, s42, s52
	v_lshl_add_u64 v[36:37], v[32:33], 0, v[176:177]
	s_mov_b32 s7, 0x8000
	s_addc_u32 s48, s43, 0
	s_lshl_b64 s[70:71], s[40:41], 1
	v_ashrrev_i32_e32 v34, 3, v18
	v_lshl_add_u64 v[30:31], s[60:61], 0, v[16:17]
	v_add_co_u32_e64 v32, s[40:41], s7, v36
	s_add_u32 s62, s37, s70
	v_lshl_add_u64 v[30:31], v[30:31], 0, v[176:177]
	v_addc_co_u32_e64 v33, s[40:41], 0, v37, s[40:41]
	v_ashrrev_i32_e32 v35, 31, v34
	s_addc_u32 s63, s48, s71
	v_and_b32_e32 v29, 7, v18
	s_waitcnt vmcnt(0)
	flat_load_dwordx4 v[96:99], v[30:31]
	flat_load_dwordx4 v[100:103], v[32:33]
	v_lshlrev_b64 v[32:33], 16, v[34:35]
	v_lshl_add_u64 v[38:39], s[62:63], 0, v[32:33]
	v_lshlrev_b32_e32 v30, 4, v29
	v_mov_b32_e32 v31, v177
	v_lshl_add_u64 v[38:39], v[38:39], 0, v[30:31]
	s_mov_b32 s7, 0xcb00000
	s_mov_b64 s[14:15], 0xcb00000
	v_add_co_u32_e64 v42, s[40:41], s7, v38
	v_lshl_add_u64 v[40:41], v[38:39], 0, s[14:15]
	s_nop 0
	v_addc_co_u32_e64 v43, s[40:41], 0, v39, s[40:41]
	s_mov_b64 s[14:15], 0xcf00000
	s_mov_b32 s7, 0xcf00000
	v_lshl_add_u64 v[44:45], v[38:39], 0, s[14:15]
	v_add_co_u32_e64 v38, s[40:41], s7, v38
	v_readlane_b32 s7, v255, 23
	s_nop 0
	v_addc_co_u32_e64 v39, s[40:41], 0, v39, s[40:41]
	v_add_co_u32_e64 v46, s[40:41], s9, v36
	s_nop 1
	v_addc_co_u32_e64 v47, s[40:41], 0, v37, s[40:41]
	v_add_co_u32_e64 v36, s[40:41], s10, v36
	s_nop 1
	v_addc_co_u32_e64 v37, s[40:41], 0, v37, s[40:41]
	flat_load_dwordx4 v[104:107], v[46:47]
	flat_load_dwordx4 v[108:111], v[36:37]
	flat_load_dwordx4 v[120:123], v[42:43]
	flat_load_dwordx4 v[112:115], v[40:41] offset:128
	flat_load_dwordx4 v[124:127], v[38:39]
	flat_load_dwordx4 v[116:119], v[44:45] offset:128
	v_add_u32_e32 v36, s7, v20
	v_mul_lo_u32 v20, v22, s12
	v_add_u32_e32 v22, v36, v20
	s_waitcnt vmcnt(0) lgkmcnt(0)
	ds_write_b128 v22, v[4:7]
	v_mad_u64_u32 v[4:5], s[40:41], v24, s12, v[36:37]
	ds_write_b128 v4, v[0:3]
	v_mad_u64_u32 v[0:1], s[40:41], v26, s12, v[36:37]
	ds_write_b128 v0, v[12:15]
	v_mad_u64_u32 v[0:1], s[40:41], v28, s12, v[36:37]
	ds_write_b128 v0, v[8:11]
	v_lshl_add_u32 v0, v18, 2, 0
	v_add_u32_e32 v1, 0x11800, v0
	ds_write_b32 v1, v21
	s_and_saveexec_b64 s[40:41], vcc
	ds_write_b32 v1, v25 offset:2048
	s_or_b64 exec, exec, s[40:41]
	s_and_saveexec_b64 s[40:41], s[0:1]
	v_add_u32_e32 v0, 0x1a900, v0
	ds_write_b32 v0, v19
	s_or_b64 exec, exec, s[40:41]
	s_ashr_i32 s60, s58, 8
	s_lshl_b32 s0, s60, 7
	s_bfe_u32 s61, s58, 0x20006
	s_add_i32 s1, s0, 0
	v_and_b32_e32 v2, 31, v18
	s_lshl_b32 s37, s61, 5
	s_add_i32 s1, s1, 0x12100
	v_or_b32_e32 v1, s37, v2
	v_mov_b32_e32 v3, s1
	v_lshlrev_b32_e32 v0, 3, v18
	v_mad_u32_u24 v3, v1, s12, v3
	v_add_u32_e32 v1, 0, v20
	s_movk_i32 s1, 0x90
	v_and_b32_e32 v0, 8, v0
	v_add_u32_e32 v239, v1, v176
	v_mul_lo_u32 v1, v34, s1
	v_and_or_b32 v0, v30, s8, v0
	v_add_u32_e32 v1, 0, v1
	v_add_u32_e32 v240, v1, v0
	s_mul_i32 s1, s60, 0x410
	v_mad_u32_u24 v0, v2, s12, 0
	s_add_i32 s62, s1, 0
	s_or_b32 s72, s37, s73
	v_add_u32_e32 v4, s0, v0
	s_lshl_b32 s0, s77, 4
	s_lshr_b32 s59, s58, 6
	s_add_i32 s62, s62, 0x11800
	s_add_i32 s63, s72, 0x9f
	s_addk_i32 s72, 0x5f
	s_and_b32 s0, s0, 0x300
	v_bfe_u32 v236, v18, 5, 1
	v_lshlrev_b32_e32 v1, 7, v2
	s_add_u32 s0, s0, s68
	v_lshlrev_b32_e32 v237, 4, v236
	v_sub_u32_e32 v0, v0, v1
	s_addc_u32 s1, 0, s69
	v_add_u32_e32 v243, v0, v237
	v_lshl_add_u64 v[0:1], s[0:1], 0, v[16:17]
	v_lshl_add_u64 v[0:1], v[0:1], 0, v[176:177]
	v_lshl_add_u64 v[0:1], s[46:47], 0, v[0:1]
	s_mov_b64 s[0:1], 0xab38000
	v_lshl_add_u64 v[190:191], v[0:1], 0, s[0:1]
	v_lshl_add_u64 v[0:1], s[52:53], 0, v[32:33]
	v_mov_b32_e32 v31, v177
	s_add_u32 s0, s42, s70
	v_lshl_add_u64 v[0:1], v[0:1], 0, v[30:31]
	s_addc_u32 s1, s43, s71
	v_lshlrev_b32_e32 v235, 2, v236
	v_lshl_add_u64 v[0:1], s[0:1], 0, v[0:1]
	s_mov_b64 s[0:1], 0xcf00180
	v_lshl_add_u64 v[192:193], v[0:1], 0, s[0:1]
	v_sub_u32_e32 v0, v235, v2
	v_subrev_u32_e32 v0, s37, v0
	s_add_i32 s0, s37, s73
	v_mov_b32_e32 v248, 0
	v_lshlrev_b32_e32 v233, 3, v27
	v_and_b32_e32 v234, 63, v18
	v_add_u32_e32 v241, 0x8800, v240
	v_add_u32_e32 v242, 0xa800, v240
	v_mul_u32_u24_e32 v238, 0x110, v2
	v_add_u32_e32 v244, 0xd000, v243
	v_subrev_u32_e32 v245, s73, v0
	s_mov_b32 s22, 0
	s_sub_i32 s46, 0, s0
	v_add_u32_e32 v246, v4, v237
	v_add_u32_e32 v247, v3, v237
	s_mov_b32 s47, 0
	v_mov_b32_e32 v0, 0
	v_mov_b32_e32 v1, v248
	v_mov_b32_e32 v2, v248
	v_mov_b32_e32 v3, v248
	v_mov_b32_e32 v4, v248
	v_mov_b32_e32 v5, v248
	v_mov_b32_e32 v6, v248
	v_mov_b32_e32 v7, v248
	v_mov_b32_e32 v8, v248
	v_mov_b32_e32 v9, v248
	v_mov_b32_e32 v10, v248
	v_mov_b32_e32 v11, v248
	v_mov_b32_e32 v12, v248
	v_mov_b32_e32 v13, v248
	v_mov_b32_e32 v14, v248
	v_mov_b32_e32 v15, v248
	v_mov_b32_e32 v16, 0
	v_mov_b32_e32 v17, v248
	v_mov_b32_e32 v18, v248
	v_mov_b32_e32 v19, v248
	v_mov_b32_e32 v20, v248
	v_mov_b32_e32 v21, v248
	v_mov_b32_e32 v22, v248
	v_mov_b32_e32 v23, v248
	v_mov_b32_e32 v24, v248
	v_mov_b32_e32 v25, v248
	v_mov_b32_e32 v26, v248
	v_mov_b32_e32 v27, v248
	v_mov_b32_e32 v28, v248
	v_mov_b32_e32 v29, v248
	v_mov_b32_e32 v30, v248
	v_mov_b32_e32 v31, v248
	v_mov_b32_e32 v32, 0
	v_mov_b32_e32 v33, v248
	v_mov_b32_e32 v34, v248
	v_mov_b32_e32 v35, v248
	v_mov_b32_e32 v36, v248
	v_mov_b32_e32 v37, v248
	v_mov_b32_e32 v38, v248
	v_mov_b32_e32 v39, v248
	v_mov_b32_e32 v40, v248
	v_mov_b32_e32 v41, v248
	v_mov_b32_e32 v42, v248
	v_mov_b32_e32 v43, v248
	v_mov_b32_e32 v44, v248
	v_mov_b32_e32 v45, v248
	v_mov_b32_e32 v46, v248
	v_mov_b32_e32 v47, v248
	v_mov_b32_e32 v48, 0
	v_mov_b32_e32 v49, v248
	v_mov_b32_e32 v50, v248
	v_mov_b32_e32 v51, v248
	v_mov_b32_e32 v52, v248
	v_mov_b32_e32 v53, v248
	v_mov_b32_e32 v54, v248
	v_mov_b32_e32 v55, v248
	v_mov_b32_e32 v56, v248
	v_mov_b32_e32 v57, v248
	v_mov_b32_e32 v58, v248
	v_mov_b32_e32 v59, v248
	v_mov_b32_e32 v60, v248
	v_mov_b32_e32 v61, v248
	v_mov_b32_e32 v62, v248
	v_mov_b32_e32 v63, v248
	ds_write_b128 v239, v[96:99]
	ds_write_b128 v239, v[100:103] offset:8704
	ds_write2_b64 v241, v[120:121], v[122:123] offset1:2
	ds_write2_b64 v242, v[124:125], v[126:127] offset0:128 offset1:130
	s_waitcnt lgkmcnt(0)
	s_barrier
	ds_read_b128 v[222:225], v247
	ds_read_b128 v[218:221], v247 offset:32
	ds_read_b128 v[214:217], v247 offset:64
	ds_read_b128 v[210:213], v247 offset:96
	s_mov_b32 s100, -1
	s_branch .LBB0_584

.LBB0_586:
	s_add_i32 s68, s46, s22
	s_setprio 1
	ds_read_b128 v[172:175], v246
	ds_read_b128 v[168:171], v246 offset:32
	ds_read_b128 v[164:167], v246 offset:64
	ds_read_b128 v[160:163], v246 offset:96
	ds_read_b128 v[156:159], v246 offset:8704
	ds_read_b128 v[152:155], v246 offset:8736
	ds_read_b128 v[148:151], v246 offset:8768
	ds_read_b128 v[144:147], v246 offset:8800
	s_cmp_lt_u32 s22, s63
	s_cselect_b64 s[42:43], -1, 0
	s_cmpk_gt_i32 s68, 0xff41
	s_cselect_b64 s[70:71], -1, 0
	s_and_b64 s[70:71], s[42:43], s[70:71]
	s_and_b64 vcc, exec, s[70:71]
	s_cbranch_vccnz .LBB0_588
	s_and_b64 s[42:43], s[42:43], exec
	s_cselect_b32 s42, 0, 0x400
	s_add_i32 s42, s62, s42
	s_cmp_eq_u32 s42, s100
	s_cbranch_scc1 .La1t0_cb
	v_mov_b32_e32 v251, s42
	ds_read_b32 v251, v251
	s_mov_b32 s100, s42
	s_waitcnt lgkmcnt(0)
	v_mov_b32_e32 v194, v251
	v_mov_b32_e32 v195, v251
	v_mov_b32_e32 v196, v251
	v_mov_b32_e32 v197, v251
	v_mov_b32_e32 v198, v251
	v_mov_b32_e32 v199, v251
	v_mov_b32_e32 v200, v251
	v_mov_b32_e32 v201, v251
	v_mov_b32_e32 v202, v251
	v_mov_b32_e32 v203, v251
	v_mov_b32_e32 v204, v251
	v_mov_b32_e32 v205, v251
	v_mov_b32_e32 v206, v251
	v_mov_b32_e32 v207, v251
	v_mov_b32_e32 v208, v251
	v_mov_b32_e32 v209, v251
	s_nop 1
.La1t0_cb:
	v_add_u32_e32 v249, s22, v245
	ds_read_b128 v[128:131], v243 offset:44032
	ds_read_b128 v[132:135], v243 offset:44064
	ds_read_b128 v[136:139], v243 offset:48640
	ds_read_b128 v[140:143], v243 offset:48672
	s_cmp_eq_u64 s[40:41], 0
	s_waitcnt lgkmcnt(11)
	v_mfma_f32_32x32x16_bf16 v[64:79], v[172:175], v[222:225], v[194:209]
	s_cbranch_scc1 .La1t0_nl0
	v_add_co_u32_e32 v186, vcc, 0xfffe8000, v190
	s_nop 1
	v_addc_co_u32_e32 v187, vcc, -1, v191, vcc
	global_load_dwordx4 v[96:99], v[186:187], off
.La1t0_nl0:
	s_waitcnt lgkmcnt(10)
	v_mfma_f32_32x32x16_bf16 v[64:79], v[168:171], v[218:221], v[64:79]
	s_cbranch_scc1 .La1t0_nl1
	v_add_co_u32_e32 v186, vcc, 0xffff0000, v190
	s_nop 1
	v_addc_co_u32_e32 v187, vcc, -1, v191, vcc
	global_load_dwordx4 v[100:103], v[186:187], off
.La1t0_nl1:
	s_waitcnt lgkmcnt(9)
	v_mfma_f32_32x32x16_bf16 v[64:79], v[164:167], v[214:217], v[64:79]
	s_cbranch_scc1 .La1t0_nl2
	v_add_co_u32_e32 v186, vcc, 0xffbfff80, v192
	s_nop 1
	v_addc_co_u32_e32 v187, vcc, -1, v193, vcc
	global_load_dwordx4 v[120:123], v[186:187], off
.La1t0_nl2:
	s_waitcnt lgkmcnt(8)
	v_mfma_f32_32x32x16_bf16 v[64:79], v[160:163], v[210:213], v[64:79]
	s_cbranch_scc1 .La1t0_nl3
	v_add_co_u32_e32 v186, vcc, 0xffffff80, v192
	s_nop 1
	v_addc_co_u32_e32 v187, vcc, -1, v193, vcc
	global_load_dwordx4 v[124:127], v[186:187], off
.La1t0_nl3:
	s_waitcnt lgkmcnt(7)
	v_mfma_f32_32x32x16_bf16 v[80:95], v[156:159], v[222:225], v[194:209]
	s_nop 11
	v_exp_f32_e32 v64, v64
	v_exp_f32_e32 v65, v65
	v_exp_f32_e32 v66, v66
	v_exp_f32_e32 v67, v67
	v_exp_f32_e32 v68, v68
	v_exp_f32_e32 v69, v69
	s_waitcnt lgkmcnt(6)
	v_mfma_f32_32x32x16_bf16 v[80:95], v[152:155], v[218:221], v[80:95]
	v_exp_f32_e32 v70, v70
	v_exp_f32_e32 v71, v71
	v_exp_f32_e32 v72, v72
	v_exp_f32_e32 v73, v73
	v_exp_f32_e32 v74, v74
	v_exp_f32_e32 v75, v75
	s_waitcnt lgkmcnt(5)
	v_mfma_f32_32x32x16_bf16 v[80:95], v[148:151], v[214:217], v[80:95]
	v_exp_f32_e32 v76, v76
	v_exp_f32_e32 v77, v77
	v_exp_f32_e32 v78, v78
	v_exp_f32_e32 v79, v79
	v_cvt_pk_bf16_f32 v160, v64, v65
	v_cvt_pk_bf16_f32 v161, v66, v67
	s_waitcnt lgkmcnt(4)
	v_mfma_f32_32x32x16_bf16 v[80:95], v[144:147], v[210:213], v[80:95]
	ds_read_b128 v[144:147], v243 offset:34816
	ds_read_b128 v[148:151], v243 offset:34848
	ds_read_b128 v[152:155], v243 offset:39424
	ds_read_b128 v[156:159], v243 offset:39456
	v_cvt_pk_bf16_f32 v162, v68, v69
	v_cvt_pk_bf16_f32 v163, v70, v71
	v_cvt_pk_bf16_f32 v164, v72, v73
	v_cvt_pk_bf16_f32 v165, v74, v75
	v_cvt_pk_bf16_f32 v166, v76, v77
	v_cvt_pk_bf16_f32 v167, v78, v79
	s_nop 4
	v_exp_f32_e32 v80, v80
	v_exp_f32_e32 v81, v81
	v_exp_f32_e32 v82, v82
	v_exp_f32_e32 v83, v83
	s_waitcnt lgkmcnt(7)
	v_mfma_f32_32x32x16_bf16 v[16:31], v[128:131], v[160:163], v[16:31]
	s_cmp_eq_u64 s[40:41], 0
	s_cbranch_scc1 .La1t0_lv_a
	s_waitcnt vmcnt(4)
	s_branch .La1t0_lv_b

.La1t0_lv_b:
	v_add_u32_e32 v251, 0xd000, v240
	ds_write_b128 v239, v[104:107] offset:17408
	ds_write_b128 v239, v[108:111] offset:26112
	ds_write2_b64 v251, v[112:113], v[114:115] offset1:2
	v_add_u32_e32 v251, 0xf000, v240
	ds_write2_b64 v251, v[116:117], v[118:119] offset0:128 offset1:130
	v_exp_f32_e32 v84, v84
	v_exp_f32_e32 v85, v85
	v_exp_f32_e32 v86, v86
	s_waitcnt lgkmcnt(6)
	v_mfma_f32_32x32x16_bf16 v[16:31], v[132:135], v[164:167], v[16:31]
	ds_read_b128 v[128:131], v243 offset:44096
	ds_read_b128 v[132:135], v243 offset:44128
	v_exp_f32_e32 v87, v87
	v_exp_f32_e32 v88, v88
	v_exp_f32_e32 v89, v89
	s_waitcnt lgkmcnt(7)
	v_mfma_f32_32x32x16_bf16 v[0:15], v[136:139], v[160:163], v[0:15]
	v_exp_f32_e32 v90, v90
	v_exp_f32_e32 v91, v91
	v_exp_f32_e32 v92, v92
	s_waitcnt lgkmcnt(6)
	v_mfma_f32_32x32x16_bf16 v[0:15], v[140:143], v[164:167], v[0:15]
	ds_read_b128 v[136:139], v243 offset:48704
	ds_read_b128 v[140:143], v243 offset:48736
	v_exp_f32_e32 v93, v93
	v_exp_f32_e32 v94, v94
	v_exp_f32_e32 v95, v95
	s_waitcnt lgkmcnt(7)
	v_mfma_f32_32x32x16_bf16 v[48:63], v[144:147], v[160:163], v[48:63]
	v_cvt_pk_bf16_f32 v168, v80, v81
	v_cvt_pk_bf16_f32 v169, v82, v83
	s_waitcnt lgkmcnt(6)
	v_mfma_f32_32x32x16_bf16 v[48:63], v[148:151], v[164:167], v[48:63]
	ds_read_b128 v[144:147], v243 offset:34880
	ds_read_b128 v[148:151], v243 offset:34912
	v_cvt_pk_bf16_f32 v170, v84, v85
	v_cvt_pk_bf16_f32 v171, v86, v87
	s_waitcnt lgkmcnt(7)
	v_mfma_f32_32x32x16_bf16 v[32:47], v[152:155], v[160:163], v[32:47]
	v_cvt_pk_bf16_f32 v172, v88, v89
	v_cvt_pk_bf16_f32 v173, v90, v91
	s_waitcnt lgkmcnt(6)
	v_mfma_f32_32x32x16_bf16 v[32:47], v[156:159], v[164:167], v[32:47]
	ds_read_b128 v[152:155], v243 offset:39488
	ds_read_b128 v[156:159], v243 offset:39520
	v_cvt_pk_bf16_f32 v174, v92, v93
	v_cvt_pk_bf16_f32 v175, v94, v95
	s_nop 1
	s_waitcnt lgkmcnt(7)
	v_mfma_f32_32x32x16_bf16 v[16:31], v[128:131], v[168:171], v[16:31]
	v_add_f32_e32 v186, v64, v67
	v_add_f32_e32 v187, v65, v68
	v_add_f32_e32 v251, v66, v69
	v_add_f32_e32 v186, v186, v70
	v_add_f32_e32 v187, v187, v71
	s_waitcnt lgkmcnt(6)
	v_mfma_f32_32x32x16_bf16 v[16:31], v[132:135], v[172:175], v[16:31]
	v_add_f32_e32 v251, v251, v72
	v_add_f32_e32 v186, v186, v73
	v_add_f32_e32 v187, v187, v74
	v_add_f32_e32 v251, v251, v75
	v_add_f32_e32 v186, v186, v76
	s_waitcnt lgkmcnt(5)
	v_mfma_f32_32x32x16_bf16 v[0:15], v[136:139], v[168:171], v[0:15]
	v_add_f32_e32 v187, v187, v77
	v_add_f32_e32 v251, v251, v78
	v_add_f32_e32 v186, v186, v79
	v_add_f32_e32 v187, v187, v80
	v_add_f32_e32 v251, v251, v81
	s_waitcnt lgkmcnt(4)
	v_mfma_f32_32x32x16_bf16 v[0:15], v[140:143], v[172:175], v[0:15]
	v_add_f32_e32 v186, v186, v82
	v_add_f32_e32 v187, v187, v83
	v_add_f32_e32 v251, v251, v84
	v_add_f32_e32 v186, v186, v85
	v_add_f32_e32 v187, v187, v86
	s_waitcnt lgkmcnt(3)
	v_mfma_f32_32x32x16_bf16 v[48:63], v[144:147], v[168:171], v[48:63]
	v_add_f32_e32 v251, v251, v87
	v_add_f32_e32 v186, v186, v88
	v_add_f32_e32 v187, v187, v89
	v_add_f32_e32 v251, v251, v90
	v_add_f32_e32 v186, v186, v91
	s_waitcnt lgkmcnt(2)
	v_mfma_f32_32x32x16_bf16 v[48:63], v[148:151], v[172:175], v[48:63]
	v_add_f32_e32 v187, v187, v92
	v_add_f32_e32 v251, v251, v93
	v_add_f32_e32 v186, v186, v94
	v_add_f32_e32 v187, v187, v95
	v_add_f32_e32 v186, v186, v187
	s_waitcnt lgkmcnt(1)
	v_mfma_f32_32x32x16_bf16 v[32:47], v[152:155], v[168:171], v[32:47]
	v_add_f32_e32 v186, v186, v251
	v_add_f32_e32 v248, v248, v186
	s_waitcnt lgkmcnt(0)
	v_mfma_f32_32x32x16_bf16 v[32:47], v[156:159], v[172:175], v[32:47]
	s_setprio 0
	s_branch .La1t0_pw
.LBB0_588:
	ds_read_b128 v[140:143], v247
	ds_read_b128 v[136:139], v247 offset:32
	ds_read_b128 v[132:135], v247 offset:64
	ds_read_b128 v[128:131], v247 offset:96
	s_cmp_eq_u64 s[40:41], 0
	s_cbranch_scc1 .La1t0_nrl
	v_add_co_u32_e32 v64, vcc, 0xfffe8000, v190
	s_nop 1
	v_addc_co_u32_e32 v65, vcc, -1, v191, vcc
	v_add_co_u32_e32 v66, vcc, 0xffff0000, v190
	s_nop 1
	v_addc_co_u32_e32 v67, vcc, -1, v191, vcc
	global_load_dwordx4 v[96:99], v[64:65], off
	global_load_dwordx4 v[100:103], v[66:67], off
	v_add_co_u32_e32 v64, vcc, 0xffbfff80, v192
	s_nop 1
	v_addc_co_u32_e32 v65, vcc, -1, v193, vcc
	v_add_co_u32_e32 v66, vcc, 0xffffff80, v192
	s_nop 1
	v_addc_co_u32_e32 v67, vcc, -1, v193, vcc
	global_load_dwordx4 v[120:123], v[64:65], off
	global_load_dwordx4 v[124:127], v[66:67], off

.LBB0_590:
	s_setprio 0
	s_waitcnt lgkmcnt(0)
	ds_read_b128 v[128:131], v243 offset:34816
	ds_read_b128 v[132:135], v243 offset:34848
	ds_read_b128 v[136:139], v243 offset:34880
	ds_read_b128 v[140:143], v243 offset:34912
	s_nop 1
	v_add_f32_e32 v64, v64, v225
	v_exp_f32_e32 v194, v64
	v_add_f32_e32 v64, v65, v225
	v_exp_f32_e32 v195, v64
	v_add_f32_e32 v64, v66, v225
	v_exp_f32_e32 v196, v64
	v_add_f32_e32 v64, v67, v225
	v_exp_f32_e32 v197, v64
	v_add_f32_e32 v64, v68, v225
	v_exp_f32_e32 v198, v64
	v_add_f32_e32 v64, v69, v225
	v_exp_f32_e32 v199, v64
	v_add_f32_e32 v64, v70, v225
	v_exp_f32_e32 v200, v64
	v_add_f32_e32 v64, v71, v225
	v_exp_f32_e32 v201, v64
	v_add_f32_e32 v64, v72, v225
	v_exp_f32_e32 v202, v64
	v_add_f32_e32 v64, v73, v225
	v_exp_f32_e32 v203, v64
	v_add_f32_e32 v64, v74, v225
	v_exp_f32_e32 v204, v64
	v_add_f32_e32 v64, v75, v225
	v_exp_f32_e32 v205, v64
	v_add_f32_e32 v64, v76, v225
	v_exp_f32_e32 v206, v64
	v_add_f32_e32 v64, v77, v225
	v_exp_f32_e32 v207, v64
	v_add_f32_e32 v64, v78, v225
	v_exp_f32_e32 v208, v64
	v_add_f32_e32 v64, v79, v225
	v_exp_f32_e32 v209, v64
	v_add_f32_e32 v64, v225, v80
	v_exp_f32_e32 v210, v64
	v_add_f32_e32 v64, v225, v81
	v_exp_f32_e32 v211, v64
	v_add_f32_e32 v64, v225, v82
	v_exp_f32_e32 v212, v64
	v_add_f32_e32 v64, v225, v83
	v_exp_f32_e32 v213, v64
	v_add_f32_e32 v64, v225, v84
	v_exp_f32_e32 v214, v64
	v_add_f32_e32 v64, v225, v85
	v_exp_f32_e32 v215, v64
	v_add_f32_e32 v64, v225, v86
	v_exp_f32_e32 v216, v64
	v_add_f32_e32 v64, v225, v87
	v_exp_f32_e32 v217, v64
	v_add_f32_e32 v64, v225, v88
	v_exp_f32_e32 v218, v64
	v_add_f32_e32 v64, v225, v89
	v_exp_f32_e32 v219, v64
	v_add_f32_e32 v64, v225, v90
	v_exp_f32_e32 v220, v64
	v_add_f32_e32 v64, v225, v91
	v_exp_f32_e32 v221, v64
	v_add_f32_e32 v64, v225, v92
	v_exp_f32_e32 v222, v64
	v_add_f32_e32 v64, v225, v93
	v_exp_f32_e32 v223, v64
	v_add_f32_e32 v64, v225, v94
	v_exp_f32_e32 v224, v64
	v_add_f32_e32 v64, v225, v95
	v_exp_f32_e32 v225, v64
	v_cvt_pk_bf16_f32 v64, v194, v195
	v_cvt_pk_bf16_f32 v65, v196, v197
	v_cvt_pk_bf16_f32 v66, v198, v199
	v_cvt_pk_bf16_f32 v67, v200, v201
	v_cvt_pk_bf16_f32 v68, v202, v203
	v_cvt_pk_bf16_f32 v69, v204, v205
	v_cvt_pk_bf16_f32 v70, v206, v207
	v_cvt_pk_bf16_f32 v71, v208, v209
	v_cvt_pk_bf16_f32 v72, v210, v211
	v_cvt_pk_bf16_f32 v73, v212, v213
	v_cvt_pk_bf16_f32 v74, v214, v215
	v_cvt_pk_bf16_f32 v75, v216, v217
	v_cvt_pk_bf16_f32 v76, v218, v219
	v_cvt_pk_bf16_f32 v77, v220, v221
	v_cvt_pk_bf16_f32 v78, v222, v223
	v_cvt_pk_bf16_f32 v79, v224, v225
	ds_read_b128 v[80:83], v243 offset:39424
	ds_read_b128 v[84:87], v243 offset:39456
	ds_read_b128 v[88:91], v243 offset:39488
	ds_read_b128 v[92:95], v243 offset:39520
	s_setprio 1
	s_waitcnt lgkmcnt(0)
	v_mfma_f32_32x32x16_bf16 v[48:63], v[128:131], v[64:67], v[48:63]
	v_mfma_f32_32x32x16_bf16 v[48:63], v[132:135], v[68:71], v[48:63]
	v_mfma_f32_32x32x16_bf16 v[48:63], v[136:139], v[72:75], v[48:63]
	v_mfma_f32_32x32x16_bf16 v[48:63], v[140:143], v[76:79], v[48:63]
	ds_read_b128 v[128:131], v243 offset:44032
	ds_read_b128 v[132:135], v243 offset:44064
	ds_read_b128 v[136:139], v243 offset:44096
	ds_read_b128 v[140:143], v243 offset:44128
	v_mfma_f32_32x32x16_bf16 v[32:47], v[80:83], v[64:67], v[32:47]
	v_mfma_f32_32x32x16_bf16 v[32:47], v[84:87], v[68:71], v[32:47]
	v_mfma_f32_32x32x16_bf16 v[32:47], v[88:91], v[72:75], v[32:47]
	v_mfma_f32_32x32x16_bf16 v[32:47], v[92:95], v[76:79], v[32:47]
	ds_read_b128 v[80:83], v243 offset:48640
	ds_read_b128 v[84:87], v243 offset:48672
	ds_read_b128 v[88:91], v243 offset:48704
	ds_read_b128 v[92:95], v243 offset:48736
	s_waitcnt lgkmcnt(0)
	v_mfma_f32_32x32x16_bf16 v[16:31], v[128:131], v[64:67], v[16:31]
	v_mfma_f32_32x32x16_bf16 v[0:15], v[80:83], v[64:67], v[0:15]
	v_mfma_f32_32x32x16_bf16 v[16:31], v[132:135], v[68:71], v[16:31]
	v_mfma_f32_32x32x16_bf16 v[0:15], v[84:87], v[68:71], v[0:15]
	v_mfma_f32_32x32x16_bf16 v[16:31], v[136:139], v[72:75], v[16:31]
	v_mfma_f32_32x32x16_bf16 v[0:15], v[88:91], v[72:75], v[0:15]
	v_mfma_f32_32x32x16_bf16 v[16:31], v[140:143], v[76:79], v[16:31]
	v_mfma_f32_32x32x16_bf16 v[0:15], v[92:95], v[76:79], v[0:15]
	s_setprio 0
	v_add_f32_e32 v128, v194, v198
	v_add_f32_e32 v129, v195, v199
	v_add_f32_e32 v130, v196, v200
	v_add_f32_e32 v131, v197, v201
	v_add_f32_e32 v128, v128, v202
	v_add_f32_e32 v129, v129, v203
	v_add_f32_e32 v130, v130, v204
	v_add_f32_e32 v131, v131, v205
	v_add_f32_e32 v128, v128, v206
	v_add_f32_e32 v129, v129, v207
	v_add_f32_e32 v130, v130, v208
	v_add_f32_e32 v131, v131, v209
	v_add_f32_e32 v128, v128, v210
	v_add_f32_e32 v129, v129, v211
	v_add_f32_e32 v130, v130, v212
	v_add_f32_e32 v131, v131, v213
	v_add_f32_e32 v128, v128, v214
	v_add_f32_e32 v129, v129, v215
	v_add_f32_e32 v130, v130, v216
	v_add_f32_e32 v131, v131, v217
	v_add_f32_e32 v128, v128, v218
	v_add_f32_e32 v129, v129, v219
	v_add_f32_e32 v130, v130, v220
	v_add_f32_e32 v131, v131, v221
	v_add_f32_e32 v128, v128, v222
	v_add_f32_e32 v129, v129, v223
	v_add_f32_e32 v130, v130, v224
	v_add_f32_e32 v131, v131, v225
	v_add_f32_e32 v128, v128, v129
	v_add_f32_e32 v128, v128, v130
	v_add_f32_e32 v128, v128, v131
	v_add_f32_e32 v248, v248, v128
	ds_read_b128 v[222:225], v247
	ds_read_b128 v[218:221], v247 offset:32
	ds_read_b128 v[214:217], v247 offset:64
	ds_read_b128 v[210:213], v247 offset:96
	s_mov_b32 s100, -1
	v_add_u32_e32 v64, 0xd000, v240
	s_cmp_eq_u64 s[40:41], 0
	s_cbranch_scc1 .La1_n0v_a
	s_waitcnt vmcnt(4)
	s_branch .La1_n0v_b

.LBB0_592:
	s_setprio 1
	ds_read_b128 v[172:175], v246 offset:17408
	ds_read_b128 v[168:171], v246 offset:17440
	ds_read_b128 v[164:167], v246 offset:17472
	ds_read_b128 v[160:163], v246 offset:17504
	ds_read_b128 v[156:159], v246 offset:26112
	ds_read_b128 v[152:155], v246 offset:26144
	ds_read_b128 v[148:151], v246 offset:26176
	ds_read_b128 v[144:147], v246 offset:26208
	s_cmp_lt_u32 s22, s72
	s_cselect_b64 s[42:43], -1, 0
	s_cmpk_gt_i32 s68, 0xff01
	s_cselect_b64 s[68:69], -1, 0
	s_and_b64 s[68:69], s[42:43], s[68:69]
	s_and_b64 vcc, exec, s[68:69]
	s_cbranch_vccnz .LBB0_594
	s_and_b64 s[42:43], s[42:43], exec
	s_cselect_b32 s42, 0, 0x400
	s_add_i32 s42, s62, s42
	s_cmp_eq_u32 s42, s100
	s_cbranch_scc1 .La1t1_cb
	v_mov_b32_e32 v251, s42
	ds_read_b32 v251, v251
	s_mov_b32 s100, s42
	s_waitcnt lgkmcnt(0)
	v_mov_b32_e32 v194, v251
	v_mov_b32_e32 v195, v251
	v_mov_b32_e32 v196, v251
	v_mov_b32_e32 v197, v251
	v_mov_b32_e32 v198, v251
	v_mov_b32_e32 v199, v251
	v_mov_b32_e32 v200, v251
	v_mov_b32_e32 v201, v251
	v_mov_b32_e32 v202, v251
	v_mov_b32_e32 v203, v251
	v_mov_b32_e32 v204, v251
	v_mov_b32_e32 v205, v251
	v_mov_b32_e32 v206, v251
	v_mov_b32_e32 v207, v251
	v_mov_b32_e32 v208, v251
	v_mov_b32_e32 v209, v251
	s_nop 1
.La1t1_cb:
	ds_read_b128 v[128:131], v243 offset:62464
	ds_read_b128 v[132:135], v243 offset:62496
	ds_read_b128 v[136:139], v244 offset:13824
	ds_read_b128 v[140:143], v244 offset:13856
	s_cmp_eq_u64 s[40:41], 0
	s_waitcnt lgkmcnt(11)
	v_mfma_f32_32x32x16_bf16 v[64:79], v[172:175], v[222:225], v[194:209]
	s_cbranch_scc1 .La1t1_nl0
	v_add_co_u32_e32 v186, vcc, 0xffff8000, v190
	s_nop 1
	v_addc_co_u32_e32 v187, vcc, -1, v191, vcc
	global_load_dwordx4 v[104:107], v[186:187], off
.La1t1_nl0:
	s_waitcnt lgkmcnt(10)
	v_mfma_f32_32x32x16_bf16 v[64:79], v[168:171], v[218:221], v[64:79]
	s_cbranch_scc1 .La1t1_nl1
	global_load_dwordx4 v[108:111], v[190:191], off
.La1t1_nl1:
	s_waitcnt lgkmcnt(9)
	v_mfma_f32_32x32x16_bf16 v[64:79], v[164:167], v[214:217], v[64:79]
	s_cbranch_scc1 .La1t1_nl2
	v_add_co_u32_e32 v186, vcc, 0xffc00000, v192
	s_nop 1
	v_addc_co_u32_e32 v187, vcc, -1, v193, vcc
	global_load_dwordx4 v[112:115], v[186:187], off
.La1t1_nl2:
	s_waitcnt lgkmcnt(8)
	v_mfma_f32_32x32x16_bf16 v[64:79], v[160:163], v[210:213], v[64:79]
	s_cbranch_scc1 .La1t1_nl3
	global_load_dwordx4 v[116:119], v[192:193], off
.La1t1_nl3:
	s_waitcnt lgkmcnt(7)
	v_mfma_f32_32x32x16_bf16 v[80:95], v[156:159], v[222:225], v[194:209]
	s_nop 11
	v_exp_f32_e32 v64, v64
	v_exp_f32_e32 v65, v65
	v_exp_f32_e32 v66, v66
	v_exp_f32_e32 v67, v67
	v_exp_f32_e32 v68, v68
	v_exp_f32_e32 v69, v69
	s_waitcnt lgkmcnt(6)
	v_mfma_f32_32x32x16_bf16 v[80:95], v[152:155], v[218:221], v[80:95]
	v_exp_f32_e32 v70, v70
	v_exp_f32_e32 v71, v71
	v_exp_f32_e32 v72, v72
	v_exp_f32_e32 v73, v73
	v_exp_f32_e32 v74, v74
	v_exp_f32_e32 v75, v75
	s_waitcnt lgkmcnt(5)
	v_mfma_f32_32x32x16_bf16 v[80:95], v[148:151], v[214:217], v[80:95]
	v_exp_f32_e32 v76, v76
	v_exp_f32_e32 v77, v77
	v_exp_f32_e32 v78, v78
	v_exp_f32_e32 v79, v79
	v_cvt_pk_bf16_f32 v160, v64, v65
	v_cvt_pk_bf16_f32 v161, v66, v67
	s_waitcnt lgkmcnt(4)
	v_mfma_f32_32x32x16_bf16 v[80:95], v[144:147], v[210:213], v[80:95]
	ds_read_b128 v[144:147], v243 offset:53248
	ds_read_b128 v[148:151], v243 offset:53280
	ds_read_b128 v[152:155], v243 offset:57856
	ds_read_b128 v[156:159], v243 offset:57888
	v_cvt_pk_bf16_f32 v162, v68, v69
	v_cvt_pk_bf16_f32 v163, v70, v71
	v_cvt_pk_bf16_f32 v164, v72, v73
	v_cvt_pk_bf16_f32 v165, v74, v75
	v_cvt_pk_bf16_f32 v166, v76, v77
	v_cvt_pk_bf16_f32 v167, v78, v79
	s_nop 4
	v_exp_f32_e32 v80, v80
	v_exp_f32_e32 v81, v81
	v_exp_f32_e32 v82, v82
	v_exp_f32_e32 v83, v83
	s_waitcnt lgkmcnt(7)
	v_mfma_f32_32x32x16_bf16 v[16:31], v[128:131], v[160:163], v[16:31]
	s_cmp_eq_u64 s[40:41], 0
	s_cbranch_scc1 .La1t1_lv_s
	s_waitcnt vmcnt(4)
	ds_write_b128 v239, v[96:99]
	ds_write_b128 v239, v[100:103] offset:8704
	ds_write2_b64 v241, v[120:121], v[122:123] offset1:2
	ds_write2_b64 v242, v[124:125], v[126:127] offset0:128 offset1:130
.La1t1_lv_s:
	v_exp_f32_e32 v84, v84
	v_exp_f32_e32 v85, v85
	v_exp_f32_e32 v86, v86
	s_waitcnt lgkmcnt(6)
	v_mfma_f32_32x32x16_bf16 v[16:31], v[132:135], v[164:167], v[16:31]
	ds_read_b128 v[128:131], v243 offset:62528
	ds_read_b128 v[132:135], v243 offset:62560
	v_exp_f32_e32 v87, v87
	v_exp_f32_e32 v88, v88
	v_exp_f32_e32 v89, v89
	s_waitcnt lgkmcnt(7)
	v_mfma_f32_32x32x16_bf16 v[0:15], v[136:139], v[160:163], v[0:15]
	v_exp_f32_e32 v90, v90
	v_exp_f32_e32 v91, v91
	v_exp_f32_e32 v92, v92
	s_waitcnt lgkmcnt(6)
	v_mfma_f32_32x32x16_bf16 v[0:15], v[140:143], v[164:167], v[0:15]
	ds_read_b128 v[136:139], v244 offset:13888
	ds_read_b128 v[140:143], v244 offset:13920
	v_exp_f32_e32 v93, v93
	v_exp_f32_e32 v94, v94
	v_exp_f32_e32 v95, v95
	s_waitcnt lgkmcnt(7)
	v_mfma_f32_32x32x16_bf16 v[48:63], v[144:147], v[160:163], v[48:63]
	v_cvt_pk_bf16_f32 v168, v80, v81
	v_cvt_pk_bf16_f32 v169, v82, v83
	s_waitcnt lgkmcnt(6)
	v_mfma_f32_32x32x16_bf16 v[48:63], v[148:151], v[164:167], v[48:63]
	ds_read_b128 v[144:147], v243 offset:53312
	ds_read_b128 v[148:151], v243 offset:53344
	v_cvt_pk_bf16_f32 v170, v84, v85
	v_cvt_pk_bf16_f32 v171, v86, v87
	s_waitcnt lgkmcnt(7)
	v_mfma_f32_32x32x16_bf16 v[32:47], v[152:155], v[160:163], v[32:47]
	v_cvt_pk_bf16_f32 v172, v88, v89
	v_cvt_pk_bf16_f32 v173, v90, v91
	s_waitcnt lgkmcnt(6)
	v_mfma_f32_32x32x16_bf16 v[32:47], v[156:159], v[164:167], v[32:47]
	ds_read_b128 v[152:155], v243 offset:57920
	ds_read_b128 v[156:159], v243 offset:57952
	v_cvt_pk_bf16_f32 v174, v92, v93
	v_cvt_pk_bf16_f32 v175, v94, v95
	s_nop 1
	s_waitcnt lgkmcnt(7)
	v_mfma_f32_32x32x16_bf16 v[16:31], v[128:131], v[168:171], v[16:31]
	v_add_f32_e32 v186, v64, v67
	v_add_f32_e32 v187, v65, v68
	v_add_f32_e32 v251, v66, v69
	v_add_f32_e32 v186, v186, v70
	v_add_f32_e32 v187, v187, v71
	s_waitcnt lgkmcnt(6)
	v_mfma_f32_32x32x16_bf16 v[16:31], v[132:135], v[172:175], v[16:31]
	v_add_f32_e32 v251, v251, v72
	v_add_f32_e32 v186, v186, v73
	v_add_f32_e32 v187, v187, v74
	v_add_f32_e32 v251, v251, v75
	v_add_f32_e32 v186, v186, v76
	s_waitcnt lgkmcnt(5)
	v_mfma_f32_32x32x16_bf16 v[0:15], v[136:139], v[168:171], v[0:15]
	v_add_f32_e32 v187, v187, v77
	v_add_f32_e32 v251, v251, v78
	v_add_f32_e32 v186, v186, v79
	v_add_f32_e32 v187, v187, v80
	v_add_f32_e32 v251, v251, v81
	s_waitcnt lgkmcnt(4)
	v_mfma_f32_32x32x16_bf16 v[0:15], v[140:143], v[172:175], v[0:15]
	v_add_f32_e32 v186, v186, v82
	v_add_f32_e32 v187, v187, v83
	v_add_f32_e32 v251, v251, v84
	v_add_f32_e32 v186, v186, v85
	v_add_f32_e32 v187, v187, v86
	s_waitcnt lgkmcnt(3)
	v_mfma_f32_32x32x16_bf16 v[48:63], v[144:147], v[168:171], v[48:63]
	v_add_f32_e32 v251, v251, v87
	v_add_f32_e32 v186, v186, v88
	v_add_f32_e32 v187, v187, v89
	v_add_f32_e32 v251, v251, v90
	v_add_f32_e32 v186, v186, v91
	s_waitcnt lgkmcnt(2)
	v_mfma_f32_32x32x16_bf16 v[48:63], v[148:151], v[172:175], v[48:63]
	v_add_f32_e32 v187, v187, v92
	v_add_f32_e32 v251, v251, v93
	v_add_f32_e32 v186, v186, v94
	v_add_f32_e32 v187, v187, v95
	v_add_f32_e32 v186, v186, v187
	s_waitcnt lgkmcnt(1)
	v_mfma_f32_32x32x16_bf16 v[32:47], v[152:155], v[168:171], v[32:47]
	v_add_f32_e32 v186, v186, v251
	v_add_f32_e32 v248, v248, v186
	s_waitcnt lgkmcnt(0)
	v_mfma_f32_32x32x16_bf16 v[32:47], v[156:159], v[172:175], v[32:47]
	s_setprio 0
	s_branch .LBB0_583
.LBB0_594:
	ds_read_b128 v[140:143], v247
	ds_read_b128 v[136:139], v247 offset:32
	ds_read_b128 v[132:135], v247 offset:64
	ds_read_b128 v[128:131], v247 offset:96
	s_cmp_eq_u64 s[40:41], 0
	s_cbranch_scc1 .La1t1_nrl
	v_add_co_u32_e32 v64, vcc, 0xffff8000, v190
	s_nop 1
	v_addc_co_u32_e32 v65, vcc, -1, v191, vcc
	global_load_dwordx4 v[104:107], v[64:65], off
	global_load_dwordx4 v[108:111], v[190:191], off
	v_add_co_u32_e32 v64, vcc, 0xffc00000, v192
	s_nop 1
	v_addc_co_u32_e32 v65, vcc, -1, v193, vcc
	global_load_dwordx4 v[112:115], v[64:65], off
	global_load_dwordx4 v[116:119], v[192:193], off

.LBB0_596:
	s_setprio 0
	s_waitcnt lgkmcnt(0)
	ds_read_b128 v[128:131], v243 offset:53248
	ds_read_b128 v[132:135], v243 offset:53280
	ds_read_b128 v[136:139], v243 offset:53312
	ds_read_b128 v[140:143], v243 offset:53344
	s_nop 2
	v_add_f32_e32 v64, v250, v64
	v_add_f32_e32 v65, v250, v65
	v_add_f32_e32 v66, v250, v66
	v_add_f32_e32 v67, v250, v67
	v_add_f32_e32 v68, v250, v68
	v_add_f32_e32 v69, v250, v69
	v_add_f32_e32 v70, v250, v70
	v_add_f32_e32 v71, v250, v71
	v_add_f32_e32 v72, v250, v72
	v_add_f32_e32 v73, v250, v73
	v_add_f32_e32 v74, v250, v74
	v_add_f32_e32 v75, v250, v75
	v_add_f32_e32 v76, v250, v76
	v_add_f32_e32 v77, v250, v77
	v_add_f32_e32 v78, v250, v78
	v_add_f32_e32 v79, v250, v79
	v_add_f32_e32 v80, v80, v250
	v_add_f32_e32 v81, v81, v250
	v_add_f32_e32 v82, v82, v250
	v_add_f32_e32 v83, v83, v250
	v_add_f32_e32 v84, v84, v250
	v_add_f32_e32 v85, v85, v250
	v_add_f32_e32 v86, v86, v250
	v_add_f32_e32 v87, v87, v250
	v_add_f32_e32 v88, v88, v250
	v_add_f32_e32 v89, v89, v250
	v_add_f32_e32 v90, v90, v250
	v_add_f32_e32 v91, v91, v250
	v_add_f32_e32 v92, v92, v250
	v_add_f32_e32 v93, v93, v250
	v_add_f32_e32 v94, v94, v250
	v_add_f32_e32 v95, v95, v250
	v_exp_f32_e32 v64, v64
	v_exp_f32_e32 v65, v65
	v_exp_f32_e32 v66, v66
	v_exp_f32_e32 v67, v67
	v_exp_f32_e32 v68, v68
	v_exp_f32_e32 v69, v69
	v_exp_f32_e32 v70, v70
	v_exp_f32_e32 v71, v71
	v_exp_f32_e32 v72, v72
	v_exp_f32_e32 v73, v73
	v_exp_f32_e32 v74, v74
	v_exp_f32_e32 v75, v75
	v_exp_f32_e32 v76, v76
	v_exp_f32_e32 v77, v77
	v_exp_f32_e32 v78, v78
	v_exp_f32_e32 v79, v79
	v_exp_f32_e32 v80, v80
	v_exp_f32_e32 v81, v81
	v_exp_f32_e32 v82, v82
	v_exp_f32_e32 v83, v83
	v_exp_f32_e32 v84, v84
	v_exp_f32_e32 v85, v85
	v_exp_f32_e32 v86, v86
	v_exp_f32_e32 v87, v87
	v_exp_f32_e32 v88, v88
	v_exp_f32_e32 v89, v89
	v_exp_f32_e32 v90, v90
	v_exp_f32_e32 v91, v91
	v_exp_f32_e32 v92, v92
	v_exp_f32_e32 v93, v93
	v_exp_f32_e32 v94, v94
	v_exp_f32_e32 v95, v95
	v_cvt_pk_bf16_f32 v144, v64, v65
	v_cvt_pk_bf16_f32 v145, v66, v67
	v_cvt_pk_bf16_f32 v146, v68, v69
	v_cvt_pk_bf16_f32 v147, v70, v71
	v_cvt_pk_bf16_f32 v148, v72, v73
	v_cvt_pk_bf16_f32 v149, v74, v75
	v_cvt_pk_bf16_f32 v150, v76, v77
	v_cvt_pk_bf16_f32 v151, v78, v79
	v_cvt_pk_bf16_f32 v152, v80, v81
	v_cvt_pk_bf16_f32 v153, v82, v83
	v_cvt_pk_bf16_f32 v154, v84, v85
	v_cvt_pk_bf16_f32 v155, v86, v87
	v_cvt_pk_bf16_f32 v156, v88, v89
	v_cvt_pk_bf16_f32 v157, v90, v91
	v_cvt_pk_bf16_f32 v158, v92, v93
	v_cvt_pk_bf16_f32 v159, v94, v95
	ds_read_b128 v[160:163], v243 offset:57856
	ds_read_b128 v[164:167], v243 offset:57888
	ds_read_b128 v[168:171], v243 offset:57920
	ds_read_b128 v[172:175], v243 offset:57952
	s_setprio 1
	s_waitcnt lgkmcnt(0)
	v_mfma_f32_32x32x16_bf16 v[48:63], v[128:131], v[144:147], v[48:63]
	v_mfma_f32_32x32x16_bf16 v[48:63], v[132:135], v[148:151], v[48:63]
	v_mfma_f32_32x32x16_bf16 v[48:63], v[136:139], v[152:155], v[48:63]
	v_mfma_f32_32x32x16_bf16 v[48:63], v[140:143], v[156:159], v[48:63]
	ds_read_b128 v[128:131], v243 offset:62464
	ds_read_b128 v[132:135], v243 offset:62496
	ds_read_b128 v[136:139], v243 offset:62528
	ds_read_b128 v[140:143], v243 offset:62560
	v_mfma_f32_32x32x16_bf16 v[32:47], v[160:163], v[144:147], v[32:47]
	v_mfma_f32_32x32x16_bf16 v[32:47], v[164:167], v[148:151], v[32:47]
	v_mfma_f32_32x32x16_bf16 v[32:47], v[168:171], v[152:155], v[32:47]
	v_mfma_f32_32x32x16_bf16 v[32:47], v[172:175], v[156:159], v[32:47]
	ds_read_b128 v[160:163], v244 offset:13824
	ds_read_b128 v[164:167], v244 offset:13856
	ds_read_b128 v[168:171], v244 offset:13888
	ds_read_b128 v[172:175], v244 offset:13920
	s_waitcnt lgkmcnt(0)
	v_mfma_f32_32x32x16_bf16 v[16:31], v[128:131], v[144:147], v[16:31]
	v_mfma_f32_32x32x16_bf16 v[0:15], v[160:163], v[144:147], v[0:15]
	v_mfma_f32_32x32x16_bf16 v[16:31], v[132:135], v[148:151], v[16:31]
	v_mfma_f32_32x32x16_bf16 v[0:15], v[164:167], v[148:151], v[0:15]
	v_mfma_f32_32x32x16_bf16 v[16:31], v[136:139], v[152:155], v[16:31]
	v_mfma_f32_32x32x16_bf16 v[0:15], v[168:171], v[152:155], v[0:15]
	v_mfma_f32_32x32x16_bf16 v[16:31], v[140:143], v[156:159], v[16:31]
	v_mfma_f32_32x32x16_bf16 v[0:15], v[172:175], v[156:159], v[0:15]
	s_setprio 0
	v_add_f32_e32 v128, v64, v68
	v_add_f32_e32 v129, v65, v69
	v_add_f32_e32 v130, v66, v70
	v_add_f32_e32 v131, v67, v71
	v_add_f32_e32 v128, v128, v72
	v_add_f32_e32 v129, v129, v73
	v_add_f32_e32 v130, v130, v74
	v_add_f32_e32 v131, v131, v75
	v_add_f32_e32 v128, v128, v76
	v_add_f32_e32 v129, v129, v77
	v_add_f32_e32 v130, v130, v78
	v_add_f32_e32 v131, v131, v79
	v_add_f32_e32 v128, v128, v80
	v_add_f32_e32 v129, v129, v81
	v_add_f32_e32 v130, v130, v82
	v_add_f32_e32 v131, v131, v83
	v_add_f32_e32 v128, v128, v84
	v_add_f32_e32 v129, v129, v85
	v_add_f32_e32 v130, v130, v86
	v_add_f32_e32 v131, v131, v87
	v_add_f32_e32 v128, v128, v88
	v_add_f32_e32 v129, v129, v89
	v_add_f32_e32 v130, v130, v90
	v_add_f32_e32 v131, v131, v91
	v_add_f32_e32 v128, v128, v92
	v_add_f32_e32 v129, v129, v93
	v_add_f32_e32 v130, v130, v94
	v_add_f32_e32 v131, v131, v95
	v_add_f32_e32 v128, v128, v129
	v_add_f32_e32 v128, v128, v130
	v_add_f32_e32 v128, v128, v131
	v_add_f32_e32 v248, v248, v128
	s_andn2_b64 vcc, exec, s[40:41]
	s_cbranch_vccnz .LBB0_583
	s_waitcnt vmcnt(4)
	ds_write_b128 v239, v[96:99]
	ds_write_b128 v239, v[100:103] offset:8704
	ds_write2_b64 v241, v[120:121], v[122:123] offset1:2
	ds_write2_b64 v242, v[124:125], v[126:127] offset0:128 offset1:130
	s_branch .LBB0_583

.LBB0_617:
	s_or_b64 exec, exec, s[70:71]
	s_ashr_i32 s41, s40, 31
	s_lshl_b64 s[70:71], s[40:41], 10
	s_add_u32 s37, s42, s70
	s_addc_u32 s48, s43, s71
	s_lshl_b32 s3, s22, 1
	s_add_u32 s37, s37, s3
	s_addc_u32 s48, s48, 0
	s_add_u32 s60, s37, 0xab00000
	s_addc_u32 s61, s48, 0
	v_and_b32_e32 v27, 15, v18
	v_lshlrev_b64 v[32:33], 10, v[22:23]
	s_lshl_b32 s52, s22, 16
	v_lshlrev_b32_e32 v176, 4, v27
	v_lshl_add_u64 v[32:33], s[60:61], 0, v[32:33]
	s_add_u32 s37, s46, s52
	v_lshl_add_u64 v[36:37], v[32:33], 0, v[176:177]
	s_mov_b32 s7, 0x8000
	s_addc_u32 s48, s47, 0
	s_lshl_b64 s[72:73], s[40:41], 1
	v_ashrrev_i32_e32 v34, 3, v18
	v_lshl_add_u64 v[30:31], s[60:61], 0, v[16:17]
	v_add_co_u32_e64 v32, s[40:41], s7, v36
	s_add_u32 s62, s37, s72
	v_lshl_add_u64 v[30:31], v[30:31], 0, v[176:177]
	v_addc_co_u32_e64 v33, s[40:41], 0, v37, s[40:41]
	v_ashrrev_i32_e32 v35, 31, v34
	s_addc_u32 s63, s48, s73
	v_and_b32_e32 v29, 7, v18
	s_waitcnt vmcnt(0)
	global_load_dwordx4 v[96:99], v[30:31], off
	global_load_dwordx4 v[100:103], v[32:33], off
	v_lshlrev_b64 v[32:33], 16, v[34:35]
	v_lshl_add_u64 v[38:39], s[62:63], 0, v[32:33]
	v_lshlrev_b32_e32 v30, 4, v29
	v_mov_b32_e32 v31, v177
	v_lshl_add_u64 v[38:39], v[38:39], 0, v[30:31]
	s_mov_b32 s7, 0xcb00000
	s_mov_b64 s[14:15], 0xcb00000
	v_add_co_u32_e64 v42, s[40:41], s7, v38
	v_lshl_add_u64 v[40:41], v[38:39], 0, s[14:15]
	s_nop 0
	v_addc_co_u32_e64 v43, s[40:41], 0, v39, s[40:41]
	s_mov_b64 s[14:15], 0xcf00000
	s_mov_b32 s7, 0xcf00000
	v_lshl_add_u64 v[44:45], v[38:39], 0, s[14:15]
	v_add_co_u32_e64 v38, s[40:41], s7, v38
	v_readlane_b32 s7, v255, 23
	s_nop 0
	v_addc_co_u32_e64 v39, s[40:41], 0, v39, s[40:41]
	v_add_co_u32_e64 v46, s[40:41], s9, v36
	s_nop 1
	v_addc_co_u32_e64 v47, s[40:41], 0, v37, s[40:41]
	v_add_co_u32_e64 v36, s[40:41], s10, v36
	s_nop 1
	v_addc_co_u32_e64 v37, s[40:41], 0, v37, s[40:41]
	global_load_dwordx4 v[104:107], v[46:47], off
	global_load_dwordx4 v[108:111], v[36:37], off
	global_load_dwordx4 v[120:123], v[42:43], off
	global_load_dwordx4 v[112:115], v[40:41], off offset:128
	global_load_dwordx4 v[124:127], v[38:39], off
	global_load_dwordx4 v[116:119], v[44:45], off offset:128
	v_add_u32_e32 v36, s7, v20
	v_mul_lo_u32 v20, v22, s12
	v_add_u32_e32 v22, v36, v20
	s_waitcnt lgkmcnt(0)
	ds_write_b128 v22, v[4:7]
	v_mad_u64_u32 v[4:5], s[40:41], v24, s12, v[36:37]
	ds_write_b128 v4, v[0:3]
	v_mad_u64_u32 v[0:1], s[40:41], v26, s12, v[36:37]
	ds_write_b128 v0, v[12:15]
	v_mad_u64_u32 v[0:1], s[40:41], v28, s12, v[36:37]
	ds_write_b128 v0, v[8:11]
	v_lshl_add_u32 v0, v18, 2, 0
	v_add_u32_e32 v1, 0x11800, v0
	ds_write_b32 v1, v21
	s_and_saveexec_b64 s[40:41], vcc
	ds_write_b32 v1, v25 offset:2048
	s_or_b64 exec, exec, s[40:41]
	s_and_saveexec_b64 s[40:41], s[0:1]
	v_add_u32_e32 v0, 0x1a900, v0
	ds_write_b32 v0, v19
	s_or_b64 exec, exec, s[40:41]
	s_ashr_i32 s60, s58, 8
	s_lshl_b32 s40, s60, 7
	s_bfe_u32 s61, s58, 0x20006
	s_add_i32 s0, s40, 0
	s_lshr_b32 s59, s58, 6
	v_and_b32_e32 v2, 31, v18
	s_lshl_b32 s37, s61, 5
	s_add_i32 s0, s0, 0x12100
	v_or_b32_e32 v1, s37, v2
	v_mov_b32_e32 v3, s0
	s_and_b64 s[0:1], s[68:69], exec
	v_lshlrev_b32_e32 v0, 3, v18
	v_mad_u32_u24 v3, v1, s12, v3
	v_add_u32_e32 v1, 0, v20
	s_movk_i32 s0, 0x90
	v_and_b32_e32 v0, 8, v0
	v_add_u32_e32 v239, v1, v176
	v_mul_lo_u32 v1, v34, s0
	v_and_or_b32 v0, v30, s8, v0
	v_add_u32_e32 v1, 0, v1
	s_mul_i32 s0, s60, 0x410
	v_bfe_u32 v236, v18, 5, 1
	s_cselect_b32 s62, 32, 64
	v_add_u32_e32 v240, v1, v0
	s_add_i32 s63, s0, 0
	s_or_b32 s69, s37, s78
	v_mad_u32_u24 v0, v2, s12, 0
	v_lshlrev_b32_e32 v1, 7, v2
	v_lshlrev_b32_e32 v237, 4, v236
	s_add_i32 s63, s63, 0x11800
	v_add_u32_e32 v4, s40, v0
	v_sub_u32_e32 v0, v0, v1
	s_add_i32 s68, s69, 0x9f
	s_addk_i32 s69, 0x5f
	v_add_u32_e32 v243, v0, v237
	v_lshl_add_u64 v[0:1], s[52:53], 0, v[32:33]
	v_mov_b32_e32 v31, v177
	s_add_u32 s0, s46, s72
	v_lshl_add_u64 v[0:1], v[0:1], 0, v[30:31]
	s_addc_u32 s1, s47, s73
	v_lshl_add_u64 v[0:1], s[0:1], 0, v[0:1]
	s_mov_b64 s[0:1], 0xcf00180
	v_lshl_add_u64 v[190:191], v[0:1], 0, s[0:1]
	s_lshl_b32 s0, s77, 3
	s_and_b32 s0, s0, 0x300
	s_add_u32 s0, s0, s70
	s_addc_u32 s1, 0, s71
	v_lshl_add_u64 v[0:1], s[0:1], 0, v[16:17]
	v_lshl_add_u64 v[0:1], v[0:1], 0, v[176:177]
	v_lshlrev_b32_e32 v235, 2, v236
	v_lshl_add_u64 v[0:1], s[42:43], 0, v[0:1]
	s_mov_b64 s[0:1], 0xab38000
	v_lshl_add_u64 v[192:193], v[0:1], 0, s[0:1]
	v_sub_u32_e32 v0, v235, v2
	v_subrev_u32_e32 v0, s37, v0
	s_add_i32 s0, s37, s78
	v_mov_b32_e32 v248, 0
	v_lshlrev_b32_e32 v233, 3, v27
	v_and_b32_e32 v234, 63, v18
	v_add_u32_e32 v241, 0x8800, v240
	v_add_u32_e32 v242, 0xa800, v240
	v_mul_u32_u24_e32 v238, 0x110, v2
	v_add_u32_e32 v244, 0xd000, v243
	s_mov_b32 s22, 3
	v_subrev_u32_e32 v245, s78, v0
	s_mov_b32 s42, 0
	s_sub_i32 s43, 0, s0
	v_add_u32_e32 v246, v4, v237
	v_add_u32_e32 v247, v3, v237
	v_mov_b32_e32 v0, 0
	v_mov_b32_e32 v1, v248
	v_mov_b32_e32 v2, v248
	v_mov_b32_e32 v3, v248
	v_mov_b32_e32 v4, v248
	v_mov_b32_e32 v5, v248
	v_mov_b32_e32 v6, v248
	v_mov_b32_e32 v7, v248
	v_mov_b32_e32 v8, v248
	v_mov_b32_e32 v9, v248
	v_mov_b32_e32 v10, v248
	v_mov_b32_e32 v11, v248
	v_mov_b32_e32 v12, v248
	v_mov_b32_e32 v13, v248
	v_mov_b32_e32 v14, v248
	v_mov_b32_e32 v15, v248
	v_mov_b32_e32 v16, 0
	v_mov_b32_e32 v17, v248
	v_mov_b32_e32 v18, v248
	v_mov_b32_e32 v19, v248
	v_mov_b32_e32 v20, v248
	v_mov_b32_e32 v21, v248
	v_mov_b32_e32 v22, v248
	v_mov_b32_e32 v23, v248
	v_mov_b32_e32 v24, v248
	v_mov_b32_e32 v25, v248
	v_mov_b32_e32 v26, v248
	v_mov_b32_e32 v27, v248
	v_mov_b32_e32 v28, v248
	v_mov_b32_e32 v29, v248
	v_mov_b32_e32 v30, v248
	v_mov_b32_e32 v31, v248
	v_mov_b32_e32 v32, 0
	v_mov_b32_e32 v33, v248
	v_mov_b32_e32 v34, v248
	v_mov_b32_e32 v35, v248
	v_mov_b32_e32 v36, v248
	v_mov_b32_e32 v37, v248
	v_mov_b32_e32 v38, v248
	v_mov_b32_e32 v39, v248
	v_mov_b32_e32 v40, v248
	v_mov_b32_e32 v41, v248
	v_mov_b32_e32 v42, v248
	v_mov_b32_e32 v43, v248
	v_mov_b32_e32 v44, v248
	v_mov_b32_e32 v45, v248
	v_mov_b32_e32 v46, v248
	v_mov_b32_e32 v47, v248
	v_mov_b32_e32 v48, 0
	v_mov_b32_e32 v49, v248
	v_mov_b32_e32 v50, v248
	v_mov_b32_e32 v51, v248
	v_mov_b32_e32 v52, v248
	v_mov_b32_e32 v53, v248
	v_mov_b32_e32 v54, v248
	v_mov_b32_e32 v55, v248
	v_mov_b32_e32 v56, v248
	v_mov_b32_e32 v57, v248
	v_mov_b32_e32 v58, v248
	v_mov_b32_e32 v59, v248
	v_mov_b32_e32 v60, v248
	v_mov_b32_e32 v61, v248
	v_mov_b32_e32 v62, v248
	v_mov_b32_e32 v63, v248
	s_waitcnt vmcnt(0)
	ds_write_b128 v239, v[96:99]
	ds_write_b128 v239, v[100:103] offset:8704
	ds_write2_b64 v241, v[120:121], v[122:123] offset1:2
	ds_write2_b64 v242, v[124:125], v[126:127] offset0:128 offset1:130
	s_waitcnt lgkmcnt(0)
	s_barrier
	ds_read_b128 v[222:225], v247
	ds_read_b128 v[218:221], v247 offset:32
	ds_read_b128 v[214:217], v247 offset:64
	ds_read_b128 v[210:213], v247 offset:96
	s_mov_b32 s100, -1
	s_branch .LBB0_623

.LBB0_625:
	s_add_i32 s47, s43, s42
	s_setprio 1
	ds_read_b128 v[172:175], v246
	ds_read_b128 v[168:171], v246 offset:32
	ds_read_b128 v[164:167], v246 offset:64
	ds_read_b128 v[160:163], v246 offset:96
	ds_read_b128 v[156:159], v246 offset:8704
	ds_read_b128 v[152:155], v246 offset:8736
	ds_read_b128 v[148:151], v246 offset:8768
	ds_read_b128 v[144:147], v246 offset:8800
	s_cmp_lt_u32 s42, s68
	s_cselect_b64 s[40:41], -1, 0
	s_cmpk_gt_i32 s47, 0xff41
	s_cselect_b64 s[70:71], -1, 0
	s_and_b64 s[70:71], s[40:41], s[70:71]
	s_and_b64 vcc, exec, s[70:71]
	s_cbranch_vccnz .LBB0_627
	s_and_b64 s[40:41], s[40:41], exec
	s_cselect_b32 s40, 0, 0x400
	s_add_i32 s40, s63, s40
	s_cmp_eq_u32 s40, s100
	s_cbranch_scc1 .La2t0_cb
	v_mov_b32_e32 v251, s40
	ds_read_b32 v251, v251
	s_mov_b32 s100, s40
	s_waitcnt lgkmcnt(0)
	v_mov_b32_e32 v194, v251
	v_mov_b32_e32 v195, v251
	v_mov_b32_e32 v196, v251
	v_mov_b32_e32 v197, v251
	v_mov_b32_e32 v198, v251
	v_mov_b32_e32 v199, v251
	v_mov_b32_e32 v200, v251
	v_mov_b32_e32 v201, v251
	v_mov_b32_e32 v202, v251
	v_mov_b32_e32 v203, v251
	v_mov_b32_e32 v204, v251
	v_mov_b32_e32 v205, v251
	v_mov_b32_e32 v206, v251
	v_mov_b32_e32 v207, v251
	v_mov_b32_e32 v208, v251
	v_mov_b32_e32 v209, v251
	s_nop 1
.La2t0_cb:
	v_add_u32_e32 v249, s42, v245
	ds_read_b128 v[128:131], v243 offset:44032
	ds_read_b128 v[132:135], v243 offset:44064
	ds_read_b128 v[136:139], v243 offset:48640
	ds_read_b128 v[140:143], v243 offset:48672
	s_cmp_eq_u64 s[0:1], 0
	s_waitcnt lgkmcnt(11)
	v_mfma_f32_32x32x16_bf16 v[64:79], v[172:175], v[222:225], v[194:209]
	s_cbranch_scc1 .La2t0_nl0
	v_add_co_u32_e32 v186, vcc, 0xfffe8000, v192
	s_nop 1
	v_addc_co_u32_e32 v187, vcc, -1, v193, vcc
	global_load_dwordx4 v[96:99], v[186:187], off
.La2t0_nl0:
	s_waitcnt lgkmcnt(10)
	v_mfma_f32_32x32x16_bf16 v[64:79], v[168:171], v[218:221], v[64:79]
	s_cbranch_scc1 .La2t0_nl1
	v_add_co_u32_e32 v186, vcc, 0xffff0000, v192
	s_nop 1
	v_addc_co_u32_e32 v187, vcc, -1, v193, vcc
	global_load_dwordx4 v[100:103], v[186:187], off
.La2t0_nl1:
	s_waitcnt lgkmcnt(9)
	v_mfma_f32_32x32x16_bf16 v[64:79], v[164:167], v[214:217], v[64:79]
	s_cbranch_scc1 .La2t0_nl2
	v_add_co_u32_e32 v186, vcc, 0xffbfff80, v190
	s_nop 1
	v_addc_co_u32_e32 v187, vcc, -1, v191, vcc
	global_load_dwordx4 v[120:123], v[186:187], off
.La2t0_nl2:
	s_waitcnt lgkmcnt(8)
	v_mfma_f32_32x32x16_bf16 v[64:79], v[160:163], v[210:213], v[64:79]
	s_cbranch_scc1 .La2t0_nl3
	v_add_co_u32_e32 v186, vcc, 0xffffff80, v190
	s_nop 1
	v_addc_co_u32_e32 v187, vcc, -1, v191, vcc
	global_load_dwordx4 v[124:127], v[186:187], off
.La2t0_nl3:
	s_waitcnt lgkmcnt(7)
	v_mfma_f32_32x32x16_bf16 v[80:95], v[156:159], v[222:225], v[194:209]
	s_nop 11
	v_exp_f32_e32 v64, v64
	v_exp_f32_e32 v65, v65
	v_exp_f32_e32 v66, v66
	v_exp_f32_e32 v67, v67
	v_exp_f32_e32 v68, v68
	v_exp_f32_e32 v69, v69
	s_waitcnt lgkmcnt(6)
	v_mfma_f32_32x32x16_bf16 v[80:95], v[152:155], v[218:221], v[80:95]
	v_exp_f32_e32 v70, v70
	v_exp_f32_e32 v71, v71
	v_exp_f32_e32 v72, v72
	v_exp_f32_e32 v73, v73
	v_exp_f32_e32 v74, v74
	v_exp_f32_e32 v75, v75
	s_waitcnt lgkmcnt(5)
	v_mfma_f32_32x32x16_bf16 v[80:95], v[148:151], v[214:217], v[80:95]
	v_exp_f32_e32 v76, v76
	v_exp_f32_e32 v77, v77
	v_exp_f32_e32 v78, v78
	v_exp_f32_e32 v79, v79
	v_cvt_pk_bf16_f32 v160, v64, v65
	v_cvt_pk_bf16_f32 v161, v66, v67
	s_waitcnt lgkmcnt(4)
	v_mfma_f32_32x32x16_bf16 v[80:95], v[144:147], v[210:213], v[80:95]
	ds_read_b128 v[144:147], v243 offset:34816
	ds_read_b128 v[148:151], v243 offset:34848
	ds_read_b128 v[152:155], v243 offset:39424
	ds_read_b128 v[156:159], v243 offset:39456
	v_cvt_pk_bf16_f32 v162, v68, v69
	v_cvt_pk_bf16_f32 v163, v70, v71
	v_cvt_pk_bf16_f32 v164, v72, v73
	v_cvt_pk_bf16_f32 v165, v74, v75
	v_cvt_pk_bf16_f32 v166, v76, v77
	v_cvt_pk_bf16_f32 v167, v78, v79
	s_nop 4
	v_exp_f32_e32 v80, v80
	v_exp_f32_e32 v81, v81
	v_exp_f32_e32 v82, v82
	v_exp_f32_e32 v83, v83
	s_waitcnt lgkmcnt(7)
	v_mfma_f32_32x32x16_bf16 v[16:31], v[128:131], v[160:163], v[16:31]
	s_cmp_eq_u64 s[0:1], 0
	s_cbranch_scc1 .La2t0_lv_a
	s_waitcnt vmcnt(4)
	s_branch .La2t0_lv_b

.LBB0_627:
	ds_read_b128 v[140:143], v247
	ds_read_b128 v[136:139], v247 offset:32
	ds_read_b128 v[132:135], v247 offset:64
	ds_read_b128 v[128:131], v247 offset:96
	s_cmp_eq_u64 s[0:1], 0
	s_cbranch_scc1 .La2t0_nrl
	v_add_co_u32_e32 v64, vcc, 0xfffe8000, v192
	s_nop 1
	v_addc_co_u32_e32 v65, vcc, -1, v193, vcc
	v_add_co_u32_e32 v66, vcc, 0xffff0000, v192
	s_nop 1
	v_addc_co_u32_e32 v67, vcc, -1, v193, vcc
	global_load_dwordx4 v[96:99], v[64:65], off
	global_load_dwordx4 v[100:103], v[66:67], off
	v_add_co_u32_e32 v64, vcc, 0xffbfff80, v190
	s_nop 1
	v_addc_co_u32_e32 v65, vcc, -1, v191, vcc
	v_add_co_u32_e32 v66, vcc, 0xffffff80, v190
	s_nop 1
	v_addc_co_u32_e32 v67, vcc, -1, v191, vcc
	global_load_dwordx4 v[120:123], v[64:65], off
	global_load_dwordx4 v[124:127], v[66:67], off

.LBB0_629:
	s_setprio 0
	s_waitcnt lgkmcnt(0)
	ds_read_b128 v[128:131], v243 offset:34816
	ds_read_b128 v[132:135], v243 offset:34848
	ds_read_b128 v[136:139], v243 offset:34880
	ds_read_b128 v[140:143], v243 offset:34912
	s_nop 1
	v_add_f32_e32 v64, v64, v225
	v_exp_f32_e32 v194, v64
	v_add_f32_e32 v64, v65, v225
	v_exp_f32_e32 v195, v64
	v_add_f32_e32 v64, v66, v225
	v_exp_f32_e32 v196, v64
	v_add_f32_e32 v64, v67, v225
	v_exp_f32_e32 v197, v64
	v_add_f32_e32 v64, v68, v225
	v_exp_f32_e32 v198, v64
	v_add_f32_e32 v64, v69, v225
	v_exp_f32_e32 v199, v64
	v_add_f32_e32 v64, v70, v225
	v_exp_f32_e32 v200, v64
	v_add_f32_e32 v64, v71, v225
	v_exp_f32_e32 v201, v64
	v_add_f32_e32 v64, v72, v225
	v_exp_f32_e32 v202, v64
	v_add_f32_e32 v64, v73, v225
	v_exp_f32_e32 v203, v64
	v_add_f32_e32 v64, v74, v225
	v_exp_f32_e32 v204, v64
	v_add_f32_e32 v64, v75, v225
	v_exp_f32_e32 v205, v64
	v_add_f32_e32 v64, v76, v225
	v_exp_f32_e32 v206, v64
	v_add_f32_e32 v64, v77, v225
	v_exp_f32_e32 v207, v64
	v_add_f32_e32 v64, v78, v225
	v_exp_f32_e32 v208, v64
	v_add_f32_e32 v64, v79, v225
	v_exp_f32_e32 v209, v64
	v_add_f32_e32 v64, v225, v80
	v_exp_f32_e32 v210, v64
	v_add_f32_e32 v64, v225, v81
	v_exp_f32_e32 v211, v64
	v_add_f32_e32 v64, v225, v82
	v_exp_f32_e32 v212, v64
	v_add_f32_e32 v64, v225, v83
	v_exp_f32_e32 v213, v64
	v_add_f32_e32 v64, v225, v84
	v_exp_f32_e32 v214, v64
	v_add_f32_e32 v64, v225, v85
	v_exp_f32_e32 v215, v64
	v_add_f32_e32 v64, v225, v86
	v_exp_f32_e32 v216, v64
	v_add_f32_e32 v64, v225, v87
	v_exp_f32_e32 v217, v64
	v_add_f32_e32 v64, v225, v88
	v_exp_f32_e32 v218, v64
	v_add_f32_e32 v64, v225, v89
	v_exp_f32_e32 v219, v64
	v_add_f32_e32 v64, v225, v90
	v_exp_f32_e32 v220, v64
	v_add_f32_e32 v64, v225, v91
	v_exp_f32_e32 v221, v64
	v_add_f32_e32 v64, v225, v92
	v_exp_f32_e32 v222, v64
	v_add_f32_e32 v64, v225, v93
	v_exp_f32_e32 v223, v64
	v_add_f32_e32 v64, v225, v94
	v_exp_f32_e32 v224, v64
	v_add_f32_e32 v64, v225, v95
	v_exp_f32_e32 v225, v64
	v_cvt_pk_bf16_f32 v64, v194, v195
	v_cvt_pk_bf16_f32 v65, v196, v197
	v_cvt_pk_bf16_f32 v66, v198, v199
	v_cvt_pk_bf16_f32 v67, v200, v201
	v_cvt_pk_bf16_f32 v68, v202, v203
	v_cvt_pk_bf16_f32 v69, v204, v205
	v_cvt_pk_bf16_f32 v70, v206, v207
	v_cvt_pk_bf16_f32 v71, v208, v209
	v_cvt_pk_bf16_f32 v72, v210, v211
	v_cvt_pk_bf16_f32 v73, v212, v213
	v_cvt_pk_bf16_f32 v74, v214, v215
	v_cvt_pk_bf16_f32 v75, v216, v217
	v_cvt_pk_bf16_f32 v76, v218, v219
	v_cvt_pk_bf16_f32 v77, v220, v221
	v_cvt_pk_bf16_f32 v78, v222, v223
	v_cvt_pk_bf16_f32 v79, v224, v225
	ds_read_b128 v[80:83], v243 offset:39424
	ds_read_b128 v[84:87], v243 offset:39456
	ds_read_b128 v[88:91], v243 offset:39488
	ds_read_b128 v[92:95], v243 offset:39520
	s_setprio 1
	s_waitcnt lgkmcnt(0)
	v_mfma_f32_32x32x16_bf16 v[48:63], v[128:131], v[64:67], v[48:63]
	v_mfma_f32_32x32x16_bf16 v[48:63], v[132:135], v[68:71], v[48:63]
	v_mfma_f32_32x32x16_bf16 v[48:63], v[136:139], v[72:75], v[48:63]
	v_mfma_f32_32x32x16_bf16 v[48:63], v[140:143], v[76:79], v[48:63]
	ds_read_b128 v[128:131], v243 offset:44032
	ds_read_b128 v[132:135], v243 offset:44064
	ds_read_b128 v[136:139], v243 offset:44096
	ds_read_b128 v[140:143], v243 offset:44128
	v_mfma_f32_32x32x16_bf16 v[32:47], v[80:83], v[64:67], v[32:47]
	v_mfma_f32_32x32x16_bf16 v[32:47], v[84:87], v[68:71], v[32:47]
	v_mfma_f32_32x32x16_bf16 v[32:47], v[88:91], v[72:75], v[32:47]
	v_mfma_f32_32x32x16_bf16 v[32:47], v[92:95], v[76:79], v[32:47]
	ds_read_b128 v[80:83], v243 offset:48640
	ds_read_b128 v[84:87], v243 offset:48672
	ds_read_b128 v[88:91], v243 offset:48704
	ds_read_b128 v[92:95], v243 offset:48736
	s_waitcnt lgkmcnt(0)
	v_mfma_f32_32x32x16_bf16 v[16:31], v[128:131], v[64:67], v[16:31]
	v_mfma_f32_32x32x16_bf16 v[0:15], v[80:83], v[64:67], v[0:15]
	v_mfma_f32_32x32x16_bf16 v[16:31], v[132:135], v[68:71], v[16:31]
	v_mfma_f32_32x32x16_bf16 v[0:15], v[84:87], v[68:71], v[0:15]
	v_mfma_f32_32x32x16_bf16 v[16:31], v[136:139], v[72:75], v[16:31]
	v_mfma_f32_32x32x16_bf16 v[0:15], v[88:91], v[72:75], v[0:15]
	v_mfma_f32_32x32x16_bf16 v[16:31], v[140:143], v[76:79], v[16:31]
	v_mfma_f32_32x32x16_bf16 v[0:15], v[92:95], v[76:79], v[0:15]
	s_setprio 0
	v_add_f32_e32 v128, v194, v198
	v_add_f32_e32 v129, v195, v199
	v_add_f32_e32 v130, v196, v200
	v_add_f32_e32 v131, v197, v201
	v_add_f32_e32 v128, v128, v202
	v_add_f32_e32 v129, v129, v203
	v_add_f32_e32 v130, v130, v204
	v_add_f32_e32 v131, v131, v205
	v_add_f32_e32 v128, v128, v206
	v_add_f32_e32 v129, v129, v207
	v_add_f32_e32 v130, v130, v208
	v_add_f32_e32 v131, v131, v209
	v_add_f32_e32 v128, v128, v210
	v_add_f32_e32 v129, v129, v211
	v_add_f32_e32 v130, v130, v212
	v_add_f32_e32 v131, v131, v213
	v_add_f32_e32 v128, v128, v214
	v_add_f32_e32 v129, v129, v215
	v_add_f32_e32 v130, v130, v216
	v_add_f32_e32 v131, v131, v217
	v_add_f32_e32 v128, v128, v218
	v_add_f32_e32 v129, v129, v219
	v_add_f32_e32 v130, v130, v220
	v_add_f32_e32 v131, v131, v221
	v_add_f32_e32 v128, v128, v222
	v_add_f32_e32 v129, v129, v223
	v_add_f32_e32 v130, v130, v224
	v_add_f32_e32 v131, v131, v225
	v_add_f32_e32 v128, v128, v129
	v_add_f32_e32 v128, v128, v130
	v_add_f32_e32 v128, v128, v131
	v_add_f32_e32 v248, v248, v128
	ds_read_b128 v[222:225], v247
	ds_read_b128 v[218:221], v247 offset:32
	ds_read_b128 v[214:217], v247 offset:64
	ds_read_b128 v[210:213], v247 offset:96
	s_mov_b32 s100, -1
	v_add_u32_e32 v64, 0xd000, v240
	s_cmp_eq_u64 s[0:1], 0
	s_cbranch_scc1 .La2_n0v_a
	s_waitcnt vmcnt(4)
	s_branch .La2_n0v_b

.LBB0_631:
	s_setprio 1
	ds_read_b128 v[172:175], v246 offset:17408
	ds_read_b128 v[168:171], v246 offset:17440
	ds_read_b128 v[164:167], v246 offset:17472
	ds_read_b128 v[160:163], v246 offset:17504
	ds_read_b128 v[156:159], v246 offset:26112
	ds_read_b128 v[152:155], v246 offset:26144
	ds_read_b128 v[148:151], v246 offset:26176
	ds_read_b128 v[144:147], v246 offset:26208
	s_cmp_lt_u32 s42, s69
	s_cselect_b64 s[40:41], -1, 0
	s_cmpk_gt_i32 s47, 0xff01
	s_cselect_b64 s[70:71], -1, 0
	s_and_b64 s[70:71], s[40:41], s[70:71]
	s_and_b64 vcc, exec, s[70:71]
	s_cbranch_vccnz .LBB0_633
	s_and_b64 s[40:41], s[40:41], exec
	s_cselect_b32 s40, 0, 0x400
	s_add_i32 s40, s63, s40
	s_cmp_eq_u32 s40, s100
	s_cbranch_scc1 .La2t1_cb
	v_mov_b32_e32 v251, s40
	ds_read_b32 v251, v251
	s_mov_b32 s100, s40
	s_waitcnt lgkmcnt(0)
	v_mov_b32_e32 v194, v251
	v_mov_b32_e32 v195, v251
	v_mov_b32_e32 v196, v251
	v_mov_b32_e32 v197, v251
	v_mov_b32_e32 v198, v251
	v_mov_b32_e32 v199, v251
	v_mov_b32_e32 v200, v251
	v_mov_b32_e32 v201, v251
	v_mov_b32_e32 v202, v251
	v_mov_b32_e32 v203, v251
	v_mov_b32_e32 v204, v251
	v_mov_b32_e32 v205, v251
	v_mov_b32_e32 v206, v251
	v_mov_b32_e32 v207, v251
	v_mov_b32_e32 v208, v251
	v_mov_b32_e32 v209, v251
	s_nop 1
.La2t1_cb:
	ds_read_b128 v[128:131], v243 offset:62464
	ds_read_b128 v[132:135], v243 offset:62496
	ds_read_b128 v[136:139], v244 offset:13824
	ds_read_b128 v[140:143], v244 offset:13856
	s_cmp_eq_u64 s[0:1], 0
	s_waitcnt lgkmcnt(11)
	v_mfma_f32_32x32x16_bf16 v[64:79], v[172:175], v[222:225], v[194:209]
	s_cbranch_scc1 .La2t1_nl0
	v_add_co_u32_e32 v186, vcc, 0xffff8000, v192
	s_nop 1
	v_addc_co_u32_e32 v187, vcc, -1, v193, vcc
	global_load_dwordx4 v[104:107], v[186:187], off
.La2t1_nl0:
	s_waitcnt lgkmcnt(10)
	v_mfma_f32_32x32x16_bf16 v[64:79], v[168:171], v[218:221], v[64:79]
	s_cbranch_scc1 .La2t1_nl1
	global_load_dwordx4 v[108:111], v[192:193], off
.La2t1_nl1:
	s_waitcnt lgkmcnt(9)
	v_mfma_f32_32x32x16_bf16 v[64:79], v[164:167], v[214:217], v[64:79]
	s_cbranch_scc1 .La2t1_nl2
	v_add_co_u32_e32 v186, vcc, 0xffc00000, v190
	s_nop 1
	v_addc_co_u32_e32 v187, vcc, -1, v191, vcc
	global_load_dwordx4 v[112:115], v[186:187], off
.La2t1_nl2:
	s_waitcnt lgkmcnt(8)
	v_mfma_f32_32x32x16_bf16 v[64:79], v[160:163], v[210:213], v[64:79]
	s_cbranch_scc1 .La2t1_nl3
	global_load_dwordx4 v[116:119], v[190:191], off
.La2t1_nl3:
	s_waitcnt lgkmcnt(7)
	v_mfma_f32_32x32x16_bf16 v[80:95], v[156:159], v[222:225], v[194:209]
	s_nop 11
	v_exp_f32_e32 v64, v64
	v_exp_f32_e32 v65, v65
	v_exp_f32_e32 v66, v66
	v_exp_f32_e32 v67, v67
	v_exp_f32_e32 v68, v68
	v_exp_f32_e32 v69, v69
	s_waitcnt lgkmcnt(6)
	v_mfma_f32_32x32x16_bf16 v[80:95], v[152:155], v[218:221], v[80:95]
	v_exp_f32_e32 v70, v70
	v_exp_f32_e32 v71, v71
	v_exp_f32_e32 v72, v72
	v_exp_f32_e32 v73, v73
	v_exp_f32_e32 v74, v74
	v_exp_f32_e32 v75, v75
	s_waitcnt lgkmcnt(5)
	v_mfma_f32_32x32x16_bf16 v[80:95], v[148:151], v[214:217], v[80:95]
	v_exp_f32_e32 v76, v76
	v_exp_f32_e32 v77, v77
	v_exp_f32_e32 v78, v78
	v_exp_f32_e32 v79, v79
	v_cvt_pk_bf16_f32 v160, v64, v65
	v_cvt_pk_bf16_f32 v161, v66, v67
	s_waitcnt lgkmcnt(4)
	v_mfma_f32_32x32x16_bf16 v[80:95], v[144:147], v[210:213], v[80:95]
	ds_read_b128 v[144:147], v243 offset:53248
	ds_read_b128 v[148:151], v243 offset:53280
	ds_read_b128 v[152:155], v243 offset:57856
	ds_read_b128 v[156:159], v243 offset:57888
	v_cvt_pk_bf16_f32 v162, v68, v69
	v_cvt_pk_bf16_f32 v163, v70, v71
	v_cvt_pk_bf16_f32 v164, v72, v73
	v_cvt_pk_bf16_f32 v165, v74, v75
	v_cvt_pk_bf16_f32 v166, v76, v77
	v_cvt_pk_bf16_f32 v167, v78, v79
	s_nop 4
	v_exp_f32_e32 v80, v80
	v_exp_f32_e32 v81, v81
	v_exp_f32_e32 v82, v82
	v_exp_f32_e32 v83, v83
	s_waitcnt lgkmcnt(7)
	v_mfma_f32_32x32x16_bf16 v[16:31], v[128:131], v[160:163], v[16:31]
	s_cmp_eq_u64 s[0:1], 0
	s_cbranch_scc1 .La2t1_lv_s
	s_waitcnt vmcnt(4)
	ds_write_b128 v239, v[96:99]
	ds_write_b128 v239, v[100:103] offset:8704
	ds_write2_b64 v241, v[120:121], v[122:123] offset1:2
	ds_write2_b64 v242, v[124:125], v[126:127] offset0:128 offset1:130

.LBB0_633:
	ds_read_b128 v[140:143], v247
	ds_read_b128 v[136:139], v247 offset:32
	ds_read_b128 v[132:135], v247 offset:64
	ds_read_b128 v[128:131], v247 offset:96
	s_cmp_eq_u64 s[0:1], 0
	s_cbranch_scc1 .La2t1_nrl
	v_add_co_u32_e32 v64, vcc, 0xffff8000, v192
	s_nop 1
	v_addc_co_u32_e32 v65, vcc, -1, v193, vcc
	global_load_dwordx4 v[104:107], v[64:65], off
	global_load_dwordx4 v[108:111], v[192:193], off
	v_add_co_u32_e32 v64, vcc, 0xffc00000, v190
	s_nop 1
	v_addc_co_u32_e32 v65, vcc, -1, v191, vcc
	global_load_dwordx4 v[112:115], v[64:65], off
	global_load_dwordx4 v[116:119], v[190:191], off

.LBB0_635:
	s_setprio 0
	s_waitcnt lgkmcnt(0)
	ds_read_b128 v[128:131], v243 offset:53248
	ds_read_b128 v[132:135], v243 offset:53280
	ds_read_b128 v[136:139], v243 offset:53312
	ds_read_b128 v[140:143], v243 offset:53344
	s_nop 2
	v_add_f32_e32 v64, v250, v64
	v_add_f32_e32 v65, v250, v65
	v_add_f32_e32 v66, v250, v66
	v_add_f32_e32 v67, v250, v67
	v_add_f32_e32 v68, v250, v68
	v_add_f32_e32 v69, v250, v69
	v_add_f32_e32 v70, v250, v70
	v_add_f32_e32 v71, v250, v71
	v_add_f32_e32 v72, v250, v72
	v_add_f32_e32 v73, v250, v73
	v_add_f32_e32 v74, v250, v74
	v_add_f32_e32 v75, v250, v75
	v_add_f32_e32 v76, v250, v76
	v_add_f32_e32 v77, v250, v77
	v_add_f32_e32 v78, v250, v78
	v_add_f32_e32 v79, v250, v79
	v_add_f32_e32 v80, v80, v250
	v_add_f32_e32 v81, v81, v250
	v_add_f32_e32 v82, v82, v250
	v_add_f32_e32 v83, v83, v250
	v_add_f32_e32 v84, v84, v250
	v_add_f32_e32 v85, v85, v250
	v_add_f32_e32 v86, v86, v250
	v_add_f32_e32 v87, v87, v250
	v_add_f32_e32 v88, v88, v250
	v_add_f32_e32 v89, v89, v250
	v_add_f32_e32 v90, v90, v250
	v_add_f32_e32 v91, v91, v250
	v_add_f32_e32 v92, v92, v250
	v_add_f32_e32 v93, v93, v250
	v_add_f32_e32 v94, v94, v250
	v_add_f32_e32 v95, v95, v250
	v_exp_f32_e32 v64, v64
	v_exp_f32_e32 v65, v65
	v_exp_f32_e32 v66, v66
	v_exp_f32_e32 v67, v67
	v_exp_f32_e32 v68, v68
	v_exp_f32_e32 v69, v69
	v_exp_f32_e32 v70, v70
	v_exp_f32_e32 v71, v71
	v_exp_f32_e32 v72, v72
	v_exp_f32_e32 v73, v73
	v_exp_f32_e32 v74, v74
	v_exp_f32_e32 v75, v75
	v_exp_f32_e32 v76, v76
	v_exp_f32_e32 v77, v77
	v_exp_f32_e32 v78, v78
	v_exp_f32_e32 v79, v79
	v_exp_f32_e32 v80, v80
	v_exp_f32_e32 v81, v81
	v_exp_f32_e32 v82, v82
	v_exp_f32_e32 v83, v83
	v_exp_f32_e32 v84, v84
	v_exp_f32_e32 v85, v85
	v_exp_f32_e32 v86, v86
	v_exp_f32_e32 v87, v87
	v_exp_f32_e32 v88, v88
	v_exp_f32_e32 v89, v89
	v_exp_f32_e32 v90, v90
	v_exp_f32_e32 v91, v91
	v_exp_f32_e32 v92, v92
	v_exp_f32_e32 v93, v93
	v_exp_f32_e32 v94, v94
	v_exp_f32_e32 v95, v95
	v_cvt_pk_bf16_f32 v144, v64, v65
	v_cvt_pk_bf16_f32 v145, v66, v67
	v_cvt_pk_bf16_f32 v146, v68, v69
	v_cvt_pk_bf16_f32 v147, v70, v71
	v_cvt_pk_bf16_f32 v148, v72, v73
	v_cvt_pk_bf16_f32 v149, v74, v75
	v_cvt_pk_bf16_f32 v150, v76, v77
	v_cvt_pk_bf16_f32 v151, v78, v79
	v_cvt_pk_bf16_f32 v152, v80, v81
	v_cvt_pk_bf16_f32 v153, v82, v83
	v_cvt_pk_bf16_f32 v154, v84, v85
	v_cvt_pk_bf16_f32 v155, v86, v87
	v_cvt_pk_bf16_f32 v156, v88, v89
	v_cvt_pk_bf16_f32 v157, v90, v91
	v_cvt_pk_bf16_f32 v158, v92, v93
	v_cvt_pk_bf16_f32 v159, v94, v95
	ds_read_b128 v[160:163], v243 offset:57856
	ds_read_b128 v[164:167], v243 offset:57888
	ds_read_b128 v[168:171], v243 offset:57920
	ds_read_b128 v[172:175], v243 offset:57952
	s_setprio 1
	s_waitcnt lgkmcnt(0)
	v_mfma_f32_32x32x16_bf16 v[48:63], v[128:131], v[144:147], v[48:63]
	v_mfma_f32_32x32x16_bf16 v[48:63], v[132:135], v[148:151], v[48:63]
	v_mfma_f32_32x32x16_bf16 v[48:63], v[136:139], v[152:155], v[48:63]
	v_mfma_f32_32x32x16_bf16 v[48:63], v[140:143], v[156:159], v[48:63]
	ds_read_b128 v[128:131], v243 offset:62464
	ds_read_b128 v[132:135], v243 offset:62496
	ds_read_b128 v[136:139], v243 offset:62528
	ds_read_b128 v[140:143], v243 offset:62560
	v_mfma_f32_32x32x16_bf16 v[32:47], v[160:163], v[144:147], v[32:47]
	v_mfma_f32_32x32x16_bf16 v[32:47], v[164:167], v[148:151], v[32:47]
	v_mfma_f32_32x32x16_bf16 v[32:47], v[168:171], v[152:155], v[32:47]
	v_mfma_f32_32x32x16_bf16 v[32:47], v[172:175], v[156:159], v[32:47]
	ds_read_b128 v[160:163], v244 offset:13824
	ds_read_b128 v[164:167], v244 offset:13856
	ds_read_b128 v[168:171], v244 offset:13888
	ds_read_b128 v[172:175], v244 offset:13920
	s_waitcnt lgkmcnt(0)
	v_mfma_f32_32x32x16_bf16 v[16:31], v[128:131], v[144:147], v[16:31]
	v_mfma_f32_32x32x16_bf16 v[0:15], v[160:163], v[144:147], v[0:15]
	v_mfma_f32_32x32x16_bf16 v[16:31], v[132:135], v[148:151], v[16:31]
	v_mfma_f32_32x32x16_bf16 v[0:15], v[164:167], v[148:151], v[0:15]
	v_mfma_f32_32x32x16_bf16 v[16:31], v[136:139], v[152:155], v[16:31]
	v_mfma_f32_32x32x16_bf16 v[0:15], v[168:171], v[152:155], v[0:15]
	v_mfma_f32_32x32x16_bf16 v[16:31], v[140:143], v[156:159], v[16:31]
	v_mfma_f32_32x32x16_bf16 v[0:15], v[172:175], v[156:159], v[0:15]
	s_setprio 0
	v_add_f32_e32 v128, v64, v68
	v_add_f32_e32 v129, v65, v69
	v_add_f32_e32 v130, v66, v70
	v_add_f32_e32 v131, v67, v71
	v_add_f32_e32 v128, v128, v72
	v_add_f32_e32 v129, v129, v73
	v_add_f32_e32 v130, v130, v74
	v_add_f32_e32 v131, v131, v75
	v_add_f32_e32 v128, v128, v76
	v_add_f32_e32 v129, v129, v77
	v_add_f32_e32 v130, v130, v78
	v_add_f32_e32 v131, v131, v79
	v_add_f32_e32 v128, v128, v80
	v_add_f32_e32 v129, v129, v81
	v_add_f32_e32 v130, v130, v82
	v_add_f32_e32 v131, v131, v83
	v_add_f32_e32 v128, v128, v84
	v_add_f32_e32 v129, v129, v85
	v_add_f32_e32 v130, v130, v86
	v_add_f32_e32 v131, v131, v87
	v_add_f32_e32 v128, v128, v88
	v_add_f32_e32 v129, v129, v89
	v_add_f32_e32 v130, v130, v90
	v_add_f32_e32 v131, v131, v91
	v_add_f32_e32 v128, v128, v92
	v_add_f32_e32 v129, v129, v93
	v_add_f32_e32 v130, v130, v94
	v_add_f32_e32 v131, v131, v95
	v_add_f32_e32 v128, v128, v129
	v_add_f32_e32 v128, v128, v130
	v_add_f32_e32 v128, v128, v131
	v_add_f32_e32 v248, v248, v128
	s_andn2_b64 vcc, exec, s[0:1]
	s_cbranch_vccnz .LBB0_622
	s_waitcnt vmcnt(4)
	ds_write_b128 v239, v[96:99]
	ds_write_b128 v239, v[100:103] offset:8704
	ds_write2_b64 v241, v[120:121], v[122:123] offset1:2
	ds_write2_b64 v242, v[124:125], v[126:127] offset0:128 offset1:130
	s_branch .LBB0_622

	.amdhsa_kernel _Z8mega_fwd4Args
		.amdhsa_group_segment_fixed_size 0
		.amdhsa_private_segment_fixed_size 0
		.amdhsa_kernarg_size 440
		.amdhsa_user_sgpr_count 2
		.amdhsa_user_sgpr_dispatch_ptr 0
		.amdhsa_user_sgpr_queue_ptr 0
		.amdhsa_user_sgpr_kernarg_segment_ptr 1
		.amdhsa_user_sgpr_dispatch_id 0
		.amdhsa_user_sgpr_kernarg_preload_length 0
		.amdhsa_user_sgpr_kernarg_preload_offset 0
		.amdhsa_user_sgpr_private_segment_size 0
		.amdhsa_uses_dynamic_stack 0
		.amdhsa_enable_private_segment 0
		.amdhsa_system_sgpr_workgroup_id_x 1
		.amdhsa_system_sgpr_workgroup_id_y 0
		.amdhsa_system_sgpr_workgroup_id_z 0
		.amdhsa_system_sgpr_workgroup_info 0
		.amdhsa_system_vgpr_workitem_id 2
		.amdhsa_next_free_vgpr 256
		.amdhsa_next_free_sgpr 102
		.amdhsa_accum_offset 256
		.amdhsa_reserve_vcc 1
		.amdhsa_float_round_mode_32 0
		.amdhsa_float_round_mode_16_64 0
		.amdhsa_float_denorm_mode_32 3
		.amdhsa_float_denorm_mode_16_64 3
		.amdhsa_dx10_clamp 1
		.amdhsa_ieee_mode 1
		.amdhsa_fp16_overflow 0
		.amdhsa_tg_split 0
		.amdhsa_exception_fp_ieee_invalid_op 0
		.amdhsa_exception_fp_denorm_src 0
		.amdhsa_exception_fp_ieee_div_zero 0
		.amdhsa_exception_fp_ieee_overflow 0
		.amdhsa_exception_fp_ieee_underflow 0
		.amdhsa_exception_fp_ieee_inexact 0
		.amdhsa_exception_int_div_zero 0
	.end_amdhsa_kernel

amdhsa.kernels:
  - .agpr_count:     0
    .args:
      - .offset:         0
        .size:           184
        .value_kind:     by_value
      - .offset:         184
        .size:           4
        .value_kind:     hidden_block_count_x
      - .offset:         188
        .size:           4
        .value_kind:     hidden_block_count_y
      - .offset:         192
        .size:           4
        .value_kind:     hidden_block_count_z
      - .offset:         196
        .size:           2
        .value_kind:     hidden_group_size_x
      - .offset:         198
        .size:           2
        .value_kind:     hidden_group_size_y
      - .offset:         200
        .size:           2
        .value_kind:     hidden_group_size_z
      - .offset:         202
        .size:           2
        .value_kind:     hidden_remainder_x
      - .offset:         204
        .size:           2
        .value_kind:     hidden_remainder_y
      - .offset:         206
        .size:           2
        .value_kind:     hidden_remainder_z
      - .offset:         224
        .size:           8
        .value_kind:     hidden_global_offset_x
      - .offset:         232
        .size:           8
        .value_kind:     hidden_global_offset_y
      - .offset:         240
        .size:           8
        .value_kind:     hidden_global_offset_z
      - .offset:         248
        .size:           2
        .value_kind:     hidden_grid_dims
      - .offset:         272
        .size:           8
        .value_kind:     hidden_multigrid_sync_arg
      - .offset:         304
        .size:           4
        .value_kind:     hidden_dynamic_lds_size
    .group_segment_fixed_size: 0
    .kernarg_segment_align: 8
    .kernarg_segment_size: 440
    .language:       OpenCL C
    .language_version:
      - 2
      - 0
    .max_flat_workgroup_size: 512
    .name:           _Z8mega_fwd4Args
    .private_segment_fixed_size: 0
    .sgpr_count:     108
    .sgpr_spill_count: 236
    .symbol:         _Z8mega_fwd4Args.kd
    .uniform_work_group_size: 1
    .uses_dynamic_stack: false
    .vgpr_count:     256
    .vgpr_spill_count: 0
    .wavefront_size: 64
